# ph4 up-projection GEMMs (UQ, UKV) also use k-block-major weights, the pipelined K loop and the peeled DMA-free tail
# baseline (speedup 1.0000x reference)
; #define LAS __attribute__((address_space(3)))
;   int tid = tid_in; asm volatile("" : "+v"(tid));
;   const int lane = tid & 63, wid = __builtin_amdgcn_readfirstlane(tid >> 6), wr = wid >> 1, wc = wid & 1;
;   const int m0 = mt * 128, n0 = nt * 256;
;   const int r = lane & 31, h = lane >> 5, key = (r >> 2) & 3;
;   constexpr int STG = 24576;
;   const int rowl = lane >> 2, cch = (lane & 3) ^ ((lane >> 4) & 3);
;   const unsigned voffA = (unsigned)(rowl * lda * 2 + cch * 16), voffB = (unsigned)(rowl * K * 2 + cch * 16);
;   const char* Abase = (const char*)(A + (size_t)m0 * lda) + (size_t)(wid * 2) * 32 * lda;
;   const char* Bbase = (const char*)(Bt + (size_t)n0 * K) + (size_t)(wid * 4) * 32 * K;
;   const size_t ablk = (size_t)32 * lda, bblk = (size_t)32 * K;
;   LAS char* lds = (LAS char*)smem;
;   LAS char* ldsA = lds + (wid * 2) * 1024;
;   LAS char* ldsB = lds + 8192 + (wid * 4) * 1024;
;     ...
;   const int x0 = ((0 + h) ^ key) * 16, x1 = ((2 + h) ^ key) * 16;
;   const int a_rd = (wr * 64 + r) * 64, b_rd = 8192 + (wc * 128 + r) * 64;
;   f32x16 acc[2][4];
; #pragma unroll
;   for (int i = 0; i < 2; ++i)
; #pragma unroll
;     for (int j = 0; j < 4; ++j)
; #pragma unroll
;       for (int e = 0; e < 16; ++e) acc[i][j][e] = 0.f;
;   const int nk = K >> 5;
;   DMA_STEP_(0, 0);
;   DMA_STEP_(1, STG);
;   asm volatile("s_waitcnt vmcnt(6)" ::: "memory");
;   __builtin_amdgcn_s_barrier();
;   asm volatile("" ::: "memory");
;   int s0 = 0, s2 = 2 * STG;
.LBB0_146:
	v_readlane_b32 s10, v252, 29
	s_cmp_ge_i32 s40, s10
	s_mov_b64 s[12:13], -1
	s_cbranch_scc0 .LBB0_150
	v_readlane_b32 s10, v252, 29
	s_sub_i32 s10, s40, s10
	v_mov_b32_e32 v189, v188
	s_bfe_u32 s11, s10, 0x5001a
	s_add_i32 s11, s10, s11
	v_readfirstlane_b32 s46, v189
	s_ashr_i32 s58, s46, 6
	s_sext_i32_i16 s11, s11
	s_lshl_b32 s42, s58, 2
	s_ashr_i32 s11, s11, 5
	v_readlane_b32 s12, v252, 18
	s_ashr_i32 s43, s42, 31
	s_lshl_b32 s12, s11, s12
	v_readlane_b32 s13, v252, 41
	s_lshl_b64 s[44:45], s[42:43], 10
	s_lshl_b32 s42, s58, 12
	s_add_i32 s12, s12, s13
	s_lshl_b32 s13, s40, 7
	s_lshl_b32 s11, s11, 10
	s_lshl_b32 s10, s10, 5
	s_add_i32 s43, s42, 16
	s_ashr_i32 s42, s46, 1
	s_lshl_b32 s12, s12, 10
	s_and_b32 s13, s13, 0x380
	s_sub_i32 s10, s10, s11
	v_and_b32_e32 v0, 31, v189
	s_andn2_b32 s42, s42, 63
	s_or_b32 s41, s12, s13
	s_and_b32 s12, s10, 0xffffff00
	v_or_b32_e32 v197, s42, v0
	s_lshl_b32 s42, s58, 7
	s_lshl_b32 s10, s58, 1
	s_ashr_i32 s13, s12, 31
	s_add_i32 s59, s43, 0x2000
	s_and_b32 s42, s42, 0x80
	s_mul_i32 s47, s41, 0x1200
	s_mul_hi_i32 s46, s41, 0x1200
	s_add_u32 s47, s18, s47
	s_mul_i32 s11, s58, 0x24000
	s_addc_u32 s56, s19, s46
	s_mul_hi_i32 s10, s10, 0x12000
	s_add_u32 s46, s47, s11
	s_addc_u32 s47, s56, s10
	s_lshl_b64 s[56:57], s[12:13], 6
	s_add_u32 s10, s20, s56
	s_addc_u32 s11, s21, s57
	v_bfe_u32 v5, v189, 2, 4
	v_lshlrev_b32_e32 v2, 4, v189
	s_add_u32 s56, s10, s44
	v_bitop3_b32 v6, v2, 48, v189 bitop3:0x48
	v_or_b32_e32 v2, s42, v0
	v_mul_u32_u24_e32 v0, 0x1200, v5
	s_addc_u32 s57, s11, s45
	s_lshl_b32 s10, s58, 11
	v_or_b32_e32 v0, v0, v6
	s_sub_i32 s44, s43, s10
	v_lshl_add_u64 v[192:193], s[46:47], 0, v[0:1]
	s_mov_b32 m0, s44
	s_mov_b64 s[10:11], 0x12000
	v_lshlrev_b32_e32 v218, 6, v2
	global_load_lds_dwordx4 v0, s[46:47]
	v_lshl_add_u64 v[2:3], v[192:193], 0, s[10:11]
	s_add_i32 m0, s44, 0x400
	v_lshl_or_b32 v0, v5, 9, v6
	v_lshl_or_b32 v10, v5, 6, v6
	v_mov_b32_e32 v11, 0
	global_load_lds_dwordx4 v[2:3], off
	v_lshl_add_u64 v[194:195], s[56:57], 0, v[10:11]
	s_mov_b32 m0, s59
	s_mov_b64 s[46:47], 0x2000
	global_load_lds_dwordx4 v[194:195], off
	global_load_lds_dwordx4 v[194:195], off offset:1024
	global_load_lds_dwordx4 v[194:195], off offset:2048
	global_load_lds_dwordx4 v[194:195], off offset:3072
	s_mov_b64 s[46:47], 0x4000
	s_mov_b64 s[10:11], 0x6000
	s_mov_b64 s[10:11], 0x12040
	s_add_i32 m0, s44, 0x6000
	v_lshl_add_u64 v[2:3], v[192:193], 0, 64
	global_load_lds_dwordx4 v[2:3], off
	v_lshl_add_u64 v[2:3], v[192:193], 0, s[10:11]
	s_add_i32 m0, s44, 0x6400
	s_mov_b64 s[46:47], 0x2040
	global_load_lds_dwordx4 v[2:3], off
	s_add_i32 m0, s43, 0x8000
	s_mov_b32 s100, 0x10000
	v_lshl_add_u64 v[2:3], v[194:195], 0, s[100:101]
	global_load_lds_dwordx4 v[2:3], off
	global_load_lds_dwordx4 v[2:3], off offset:1024
	global_load_lds_dwordx4 v[2:3], off offset:2048
	global_load_lds_dwordx4 v[2:3], off offset:3072
	s_mov_b64 s[46:47], 0x4040
	s_mov_b64 s[10:11], 0x6040
	v_bfe_u32 v196, v189, 5, 1
	v_bfe_u32 v5, v189, 2, 2
	v_lshrrev_b32_e32 v4, 2, v189
	s_lshl_b32 s100, s100, 1
	v_lshl_add_u64 v[194:195], v[194:195], 0, s[100:101]
	s_waitcnt vmcnt(6)
	s_barrier
	v_bitop3_b32 v2, v196, v5, 2 bitop3:0x36
	v_bitop3_b32 v0, v196, v4, 3 bitop3:0x78
	v_lshlrev_b32_e32 v220, 4, v2
	v_mov_b32_e32 v2, 0
	v_lshlrev_b32_e32 v219, 6, v197
	v_lshlrev_b32_e32 v0, 4, v0
	s_mov_b32 s46, 0xc000
	s_mov_b32 s45, 0
	s_mov_b32 s47, 0
	v_mov_b32_e32 v3, v2
	v_mov_b32_e32 v4, v2
	v_mov_b32_e32 v5, v2
	v_mov_b32_e32 v6, v2
	v_mov_b32_e32 v7, v2
	v_mov_b32_e32 v8, v2
	v_mov_b32_e32 v9, v2
	v_mov_b32_e32 v10, v2
	v_mov_b32_e32 v11, v2
	v_mov_b32_e32 v12, v2
	v_mov_b32_e32 v13, v2
	v_mov_b32_e32 v14, v2
	v_mov_b32_e32 v15, v2
	v_mov_b32_e32 v16, v2
	v_mov_b32_e32 v17, v2
	v_mov_b32_e32 v18, v2
	v_mov_b32_e32 v19, v2
	v_mov_b32_e32 v20, v2
	v_mov_b32_e32 v21, v2
	v_mov_b32_e32 v22, v2
	v_mov_b32_e32 v23, v2
	v_mov_b32_e32 v24, v2
	v_mov_b32_e32 v25, v2
	v_mov_b32_e32 v26, v2
	v_mov_b32_e32 v27, v2
	v_mov_b32_e32 v28, v2
	v_mov_b32_e32 v29, v2
	v_mov_b32_e32 v30, v2
	v_mov_b32_e32 v31, v2
	v_mov_b32_e32 v32, v2
	v_mov_b32_e32 v33, v2
	v_mov_b32_e32 v50, v2
	v_mov_b32_e32 v51, v2
	v_mov_b32_e32 v52, v2
	v_mov_b32_e32 v53, v2
	v_mov_b32_e32 v54, v2
	v_mov_b32_e32 v55, v2
	v_mov_b32_e32 v56, v2
	v_mov_b32_e32 v57, v2
	v_mov_b32_e32 v58, v2
	v_mov_b32_e32 v59, v2
	v_mov_b32_e32 v60, v2
	v_mov_b32_e32 v61, v2
	v_mov_b32_e32 v62, v2
	v_mov_b32_e32 v63, v2
	v_mov_b32_e32 v64, v2
	v_mov_b32_e32 v65, v2
	v_mov_b32_e32 v82, v2
	v_mov_b32_e32 v83, v2
	v_mov_b32_e32 v84, v2
	v_mov_b32_e32 v85, v2
	v_mov_b32_e32 v86, v2
	v_mov_b32_e32 v87, v2
	v_mov_b32_e32 v88, v2
	v_mov_b32_e32 v89, v2
	v_mov_b32_e32 v90, v2
	v_mov_b32_e32 v91, v2
	v_mov_b32_e32 v92, v2
	v_mov_b32_e32 v93, v2
	v_mov_b32_e32 v94, v2
	v_mov_b32_e32 v95, v2
	v_mov_b32_e32 v96, v2
	v_mov_b32_e32 v97, v2
	v_mov_b32_e32 v34, v2
	v_mov_b32_e32 v35, v2
	v_mov_b32_e32 v36, v2
	v_mov_b32_e32 v37, v2
	v_mov_b32_e32 v38, v2
	v_mov_b32_e32 v39, v2
	v_mov_b32_e32 v40, v2
	v_mov_b32_e32 v41, v2
	v_mov_b32_e32 v42, v2
	v_mov_b32_e32 v43, v2
	v_mov_b32_e32 v44, v2
	v_mov_b32_e32 v45, v2
	v_mov_b32_e32 v46, v2
	v_mov_b32_e32 v47, v2
	v_mov_b32_e32 v48, v2
	v_mov_b32_e32 v49, v2
	v_mov_b32_e32 v66, v2
	v_mov_b32_e32 v67, v2
	v_mov_b32_e32 v68, v2
	v_mov_b32_e32 v69, v2
	v_mov_b32_e32 v70, v2
	v_mov_b32_e32 v71, v2
	v_mov_b32_e32 v72, v2
	v_mov_b32_e32 v73, v2
	v_mov_b32_e32 v74, v2
	v_mov_b32_e32 v75, v2
	v_mov_b32_e32 v76, v2
	v_mov_b32_e32 v77, v2
	v_mov_b32_e32 v78, v2
	v_mov_b32_e32 v79, v2
	v_mov_b32_e32 v80, v2
	v_mov_b32_e32 v81, v2
	v_mov_b32_e32 v98, v2
	v_mov_b32_e32 v99, v2
	v_mov_b32_e32 v100, v2
	v_mov_b32_e32 v101, v2
	v_mov_b32_e32 v102, v2
	v_mov_b32_e32 v103, v2
	v_mov_b32_e32 v104, v2
	v_mov_b32_e32 v105, v2
	v_mov_b32_e32 v106, v2
	v_mov_b32_e32 v107, v2
	v_mov_b32_e32 v108, v2
	v_mov_b32_e32 v109, v2
	v_mov_b32_e32 v110, v2
	v_mov_b32_e32 v111, v2
	v_mov_b32_e32 v112, v2
	v_mov_b32_e32 v113, v2
	v_mov_b32_e32 v114, v2
	v_mov_b32_e32 v115, v2
	v_mov_b32_e32 v116, v2
	v_mov_b32_e32 v117, v2
	v_mov_b32_e32 v118, v2
	v_mov_b32_e32 v119, v2
	v_mov_b32_e32 v120, v2
	v_mov_b32_e32 v121, v2
	v_mov_b32_e32 v122, v2
	v_mov_b32_e32 v123, v2
	v_mov_b32_e32 v124, v2
	v_mov_b32_e32 v125, v2
	v_mov_b32_e32 v126, v2
	v_mov_b32_e32 v127, v2
	v_mov_b32_e32 v128, v2
	v_mov_b32_e32 v129, v2
	s_mov_b64 s[56:57], 0x2080
	s_mov_b64 s[58:59], 0x4080
	v_add_u32_e32 v158, 16, v219
	v_add_u32_e32 v170, 16, v218
	v_add_u32_e32 v158, v158, v0
	v_add_u32_e32 v170, v170, v0
	ds_read_b128 v[154:157], v158
	ds_read_b128 v[182:185], v170 offset:8192
	ds_read_b128 v[178:181], v170 offset:10240
	ds_read_b128 v[158:161], v158 offset:2048
	ds_read_b128 v[174:177], v170 offset:12288
	ds_read_b128 v[170:173], v170 offset:14336
	s_setprio 1
; #define LAS __attribute__((address_space(3)))
; DI f32x16 mfma32(bf16x8 a, bf16x8 b, f32x16 c) { return __builtin_amdgcn_mfma_f32_32x32x16_bf16(a, b, c, 0, 0, 0); }
;     ...
;   for (int kt = 0; kt < nk; ++kt) {
;     const int kn = (kt + 2 < nk) ? (kt + 2) : (nk - 1);
;     const LAS char* cur = lds + s0;
;     bf16x8 af[2][2], bfr[2][4];
; #pragma unroll
;     for (int kk = 0; kk < 2; ++kk) {
;       const int xo = kk ? x1 : x0;
;       af[kk][0] = *(const LAS bf16x8*)(cur + a_rd + xo);
;       bfr[kk][0] = *(const LAS bf16x8*)(cur + b_rd + xo);
;       bfr[kk][1] = *(const LAS bf16x8*)(cur + b_rd + 2048 + xo);
;       af[kk][1] = *(const LAS bf16x8*)(cur + a_rd + 2048 + xo);
;       bfr[kk][2] = *(const LAS bf16x8*)(cur + b_rd + 4096 + xo);
;       bfr[kk][3] = *(const LAS bf16x8*)(cur + b_rd + 6144 + xo);
;     }
;     DMA_STEP_(kn, s2);
; #pragma unroll
;     for (int kk = 0; kk < 2; ++kk) {
;       acc[0][0] = mfma32(bfr[kk][0], af[kk][0], acc[0][0]); acc[0][1] = mfma32(bfr[kk][1], af[kk][0], acc[0][1]);
;       acc[1][0] = mfma32(bfr[kk][0], af[kk][1], acc[1][0]); acc[1][1] = mfma32(bfr[kk][1], af[kk][1], acc[1][1]);
;       acc[0][2] = mfma32(bfr[kk][2], af[kk][0], acc[0][2]); acc[0][3] = mfma32(bfr[kk][3], af[kk][0], acc[0][3]);
;       acc[1][2] = mfma32(bfr[kk][2], af[kk][1], acc[1][2]); acc[1][3] = mfma32(bfr[kk][3], af[kk][1], acc[1][3]);
;     }
;     __builtin_amdgcn_sched_group_barrier(0x100, 12, 0);
;     __builtin_amdgcn_sched_group_barrier(0x010, 6, 0);
;     __builtin_amdgcn_sched_group_barrier(0x008, 16, 0);
;     asm volatile("s_waitcnt vmcnt(6) lgkmcnt(0)" ::: "memory");
;     __builtin_amdgcn_s_barrier();
;     asm volatile("" ::: "memory");
;     s0 = (s0 == 2 * STG) ? 0 : s0 + STG;
;     s2 = (s2 == 2 * STG) ? 0 : s2 + STG;
;   }
.LBB0_148:
	s_add_i32 s11, s47, 16
	s_mov_b32 s10, s45
	v_add_u32_e32 v142, s11, v219
	v_add_u32_e32 v150, s11, v218
	s_min_u32 s10, s10, 5
	v_add_u32_e32 v142, v142, v220
	v_add_u32_e32 v150, v150, v220
	s_lshl_b32 s70, s10, 6
	ds_read_b128 v[138:141], v142
	ds_read_b128 v[162:165], v150 offset:8192
	ds_read_b128 v[166:169], v150 offset:10240
	ds_read_b128 v[142:145], v142 offset:2048
	ds_read_b128 v[146:149], v150 offset:12288
	ds_read_b128 v[150:153], v150 offset:14336
	v_lshl_add_u64 v[222:223], v[192:193], 0, s[70:71]
	s_add_i32 s10, s44, s46
	v_lshl_add_u64 v[224:225], v[222:223], 0, s[24:25]
	s_mov_b32 m0, s10
	v_lshl_add_u64 v[222:223], v[222:223], 0, s[36:37]
	s_mul_i32 s100, s70, 0x400
	s_waitcnt lgkmcnt(6)
	v_mfma_f32_32x32x16_bf16 v[114:129], v[182:185], v[154:157], v[114:129]
	global_load_lds_dwordx4 v[224:225], off
	s_add_i32 m0, s10, 0x400
	v_mfma_f32_32x32x16_bf16 v[98:113], v[178:181], v[154:157], v[98:113]
	global_load_lds_dwordx4 v[222:223], off
	v_lshl_add_u64 v[224:225], v[194:195], 0, s[100:101]
	s_add_i32 s10, s43, s46
	s_add_i32 m0, s10, 0x2000
	v_mfma_f32_32x32x16_bf16 v[66:81], v[182:185], v[158:161], v[66:81]
	global_load_lds_dwordx4 v[224:225], off
	v_mfma_f32_32x32x16_bf16 v[34:49], v[178:181], v[158:161], v[34:49]
	global_load_lds_dwordx4 v[224:225], off offset:1024
	v_mfma_f32_32x32x16_bf16 v[82:97], v[174:177], v[154:157], v[82:97]
	global_load_lds_dwordx4 v[224:225], off offset:2048
	v_mfma_f32_32x32x16_bf16 v[50:65], v[170:173], v[154:157], v[50:65]
	global_load_lds_dwordx4 v[224:225], off offset:3072
	v_mfma_f32_32x32x16_bf16 v[18:33], v[174:177], v[158:161], v[18:33]
	s_add_i32 s10, s47, 0x6000
	s_cmpk_lg_u32 s47, 0xc000
	s_cselect_b32 s47, s10, 0
	s_add_i32 s10, s46, 0x6000
	s_cmpk_lg_u32 s46, 0xc000
	s_cselect_b32 s46, s10, 0
	v_mfma_f32_32x32x16_bf16 v[2:17], v[170:173], v[158:161], v[2:17]
	s_add_i32 s11, s47, 16
	s_waitcnt vmcnt(6) lgkmcnt(0)
	s_barrier
	v_add_u32_e32 v158, s11, v219
	v_add_u32_e32 v170, s11, v218
	v_add_u32_e32 v158, v158, v0
	v_add_u32_e32 v170, v170, v0
	ds_read_b128 v[154:157], v158
	ds_read_b128 v[182:185], v170 offset:8192
	ds_read_b128 v[178:181], v170 offset:10240
	ds_read_b128 v[158:161], v158 offset:2048
	ds_read_b128 v[174:177], v170 offset:12288
	ds_read_b128 v[170:173], v170 offset:14336
	v_mfma_f32_32x32x16_bf16 v[114:129], v[162:165], v[138:141], v[114:129]
	v_mfma_f32_32x32x16_bf16 v[98:113], v[166:169], v[138:141], v[98:113]
	v_mfma_f32_32x32x16_bf16 v[66:81], v[162:165], v[142:145], v[66:81]
	v_mfma_f32_32x32x16_bf16 v[34:49], v[166:169], v[142:145], v[34:49]
	v_mfma_f32_32x32x16_bf16 v[82:97], v[146:149], v[138:141], v[82:97]
	v_mfma_f32_32x32x16_bf16 v[50:65], v[150:153], v[138:141], v[50:65]
	v_mfma_f32_32x32x16_bf16 v[18:33], v[146:149], v[142:145], v[18:33]
	v_mfma_f32_32x32x16_bf16 v[2:17], v[150:153], v[142:145], v[2:17]
	s_add_i32 s11, s47, 16
	s_add_i32 s10, s45, 1
	v_add_u32_e32 v142, s11, v219
	v_add_u32_e32 v150, s11, v218
	s_min_u32 s10, s10, 5
	v_add_u32_e32 v142, v142, v220
	v_add_u32_e32 v150, v150, v220
	s_lshl_b32 s70, s10, 6
	ds_read_b128 v[138:141], v142
	ds_read_b128 v[162:165], v150 offset:8192
	ds_read_b128 v[166:169], v150 offset:10240
	ds_read_b128 v[142:145], v142 offset:2048
	ds_read_b128 v[146:149], v150 offset:12288
	ds_read_b128 v[150:153], v150 offset:14336
	v_lshl_add_u64 v[222:223], v[192:193], 0, s[70:71]
	s_add_i32 s10, s44, s46
	v_lshl_add_u64 v[224:225], v[222:223], 0, s[24:25]
	s_mov_b32 m0, s10
	v_lshl_add_u64 v[222:223], v[222:223], 0, s[36:37]
	s_mul_i32 s100, s70, 0x400
	s_waitcnt lgkmcnt(6)
	v_mfma_f32_32x32x16_bf16 v[114:129], v[182:185], v[154:157], v[114:129]
	global_load_lds_dwordx4 v[224:225], off
	s_add_i32 m0, s10, 0x400
	v_mfma_f32_32x32x16_bf16 v[98:113], v[178:181], v[154:157], v[98:113]
	global_load_lds_dwordx4 v[222:223], off
	v_lshl_add_u64 v[224:225], v[194:195], 0, s[100:101]
	s_add_i32 s10, s43, s46
	s_add_i32 m0, s10, 0x2000
	v_mfma_f32_32x32x16_bf16 v[66:81], v[182:185], v[158:161], v[66:81]
	global_load_lds_dwordx4 v[224:225], off
	v_mfma_f32_32x32x16_bf16 v[34:49], v[178:181], v[158:161], v[34:49]
	global_load_lds_dwordx4 v[224:225], off offset:1024
	v_mfma_f32_32x32x16_bf16 v[82:97], v[174:177], v[154:157], v[82:97]
	global_load_lds_dwordx4 v[224:225], off offset:2048
	v_mfma_f32_32x32x16_bf16 v[50:65], v[170:173], v[154:157], v[50:65]
	global_load_lds_dwordx4 v[224:225], off offset:3072
	v_mfma_f32_32x32x16_bf16 v[18:33], v[174:177], v[158:161], v[18:33]
	s_add_i32 s10, s47, 0x6000
	s_cmpk_lg_u32 s47, 0xc000
	s_cselect_b32 s47, s10, 0
	s_add_i32 s10, s46, 0x6000
	s_cmpk_lg_u32 s46, 0xc000
	s_cselect_b32 s46, s10, 0
	v_mfma_f32_32x32x16_bf16 v[2:17], v[170:173], v[158:161], v[2:17]
	s_add_i32 s11, s47, 16
	s_waitcnt vmcnt(6) lgkmcnt(0)
	s_barrier
	v_add_u32_e32 v158, s11, v219
	v_add_u32_e32 v170, s11, v218
	v_add_u32_e32 v158, v158, v0
	v_add_u32_e32 v170, v170, v0
	ds_read_b128 v[154:157], v158
	ds_read_b128 v[182:185], v170 offset:8192
	ds_read_b128 v[178:181], v170 offset:10240
	ds_read_b128 v[158:161], v158 offset:2048
	ds_read_b128 v[174:177], v170 offset:12288
	ds_read_b128 v[170:173], v170 offset:14336
	v_mfma_f32_32x32x16_bf16 v[114:129], v[162:165], v[138:141], v[114:129]
	v_mfma_f32_32x32x16_bf16 v[98:113], v[166:169], v[138:141], v[98:113]
	v_mfma_f32_32x32x16_bf16 v[66:81], v[162:165], v[142:145], v[66:81]
	v_mfma_f32_32x32x16_bf16 v[34:49], v[166:169], v[142:145], v[34:49]
	v_mfma_f32_32x32x16_bf16 v[82:97], v[146:149], v[138:141], v[82:97]
	v_mfma_f32_32x32x16_bf16 v[50:65], v[150:153], v[138:141], v[50:65]
	v_mfma_f32_32x32x16_bf16 v[18:33], v[146:149], v[142:145], v[18:33]
	v_mfma_f32_32x32x16_bf16 v[2:17], v[150:153], v[142:145], v[2:17]
	s_add_i32 s45, s45, 2
	s_cmp_lg_u32 s45, 6
	s_cbranch_scc1 .LBB0_148
; #define LAS __attribute__((address_space(3)))
; DI unsigned pk2(float a, float b) { f32x2 v = {a, b}; bf2_t r = __builtin_convertvector(v, bf2_t); return __builtin_bit_cast(unsigned, r); }
;     ...
;   for (int kt = 0; kt < nk; ++kt) {
;     const int kn = (kt + 2 < nk) ? (kt + 2) : (nk - 1);
;     const LAS char* cur = lds + s0;
;     bf16x8 af[2][2], bfr[2][4];
; #pragma unroll
;     for (int kk = 0; kk < 2; ++kk) {
;       const int xo = kk ? x1 : x0;
;       af[kk][0] = *(const LAS bf16x8*)(cur + a_rd + xo);
;       bfr[kk][0] = *(const LAS bf16x8*)(cur + b_rd + xo);
;       bfr[kk][1] = *(const LAS bf16x8*)(cur + b_rd + 2048 + xo);
;       af[kk][1] = *(const LAS bf16x8*)(cur + a_rd + 2048 + xo);
;       bfr[kk][2] = *(const LAS bf16x8*)(cur + b_rd + 4096 + xo);
;       bfr[kk][3] = *(const LAS bf16x8*)(cur + b_rd + 6144 + xo);
;     }
;     DMA_STEP_(kn, s2);
; #pragma unroll
;     for (int kk = 0; kk < 2; ++kk) {
;       acc[0][0] = mfma32(bfr[kk][0], af[kk][0], acc[0][0]); acc[0][1] = mfma32(bfr[kk][1], af[kk][0], acc[0][1]);
;       acc[1][0] = mfma32(bfr[kk][0], af[kk][1], acc[1][0]); acc[1][1] = mfma32(bfr[kk][1], af[kk][1], acc[1][1]);
;       acc[0][2] = mfma32(bfr[kk][2], af[kk][0], acc[0][2]); acc[0][3] = mfma32(bfr[kk][3], af[kk][0], acc[0][3]);
;       acc[1][2] = mfma32(bfr[kk][2], af[kk][1], acc[1][2]); acc[1][3] = mfma32(bfr[kk][3], af[kk][1], acc[1][3]);
;     }
;     __builtin_amdgcn_sched_group_barrier(0x100, 12, 0);
;     __builtin_amdgcn_sched_group_barrier(0x010, 6, 0);
;     __builtin_amdgcn_sched_group_barrier(0x008, 16, 0);
;     asm volatile("s_waitcnt vmcnt(6) lgkmcnt(0)" ::: "memory");
;     __builtin_amdgcn_s_barrier();
;     asm volatile("" ::: "memory");
;     s0 = (s0 == 2 * STG) ? 0 : s0 + STG;
;     s2 = (s2 == 2 * STG) ? 0 : s2 + STG;
;   }
;   asm volatile("s_waitcnt vmcnt(0)" ::: "memory");
;   __builtin_amdgcn_s_barrier();
;   asm volatile("" ::: "memory");
;     ...
;   {
;     const int h = lane >> 5, cl = lane & 31;
; #pragma unroll
;     for (int i = 0; i < 2; ++i)
; #pragma unroll
;       for (int j = 0; j < 4; ++j)
; #pragma unroll
;         for (int g = 0; g < 4; ++g) {
;           u32x2 w; w.x = pk2(acc[i][j][4 * g], acc[i][j][4 * g + 1]); w.y = pk2(acc[i][j][4 * g + 2], acc[i][j][4 * g + 3]);
;           *(u32x2*)(smem + (wr * 64 + i * 32 + cl) * 528 + (wc * 128 + j * 32 + 8 * g + 4 * h) * 2) = w;
	s_add_i32 s11, s47, 16
	v_add_u32_e32 v142, s11, v219
	v_add_u32_e32 v150, s11, v218
	v_add_u32_e32 v142, v142, v220
	v_add_u32_e32 v150, v150, v220
	ds_read_b128 v[138:141], v142
	ds_read_b128 v[162:165], v150 offset:8192
	ds_read_b128 v[166:169], v150 offset:10240
	ds_read_b128 v[142:145], v142 offset:2048
	ds_read_b128 v[146:149], v150 offset:12288
	ds_read_b128 v[150:153], v150 offset:14336
	s_waitcnt lgkmcnt(6)
	v_mfma_f32_32x32x16_bf16 v[114:129], v[182:185], v[154:157], v[114:129]
	v_mfma_f32_32x32x16_bf16 v[98:113], v[178:181], v[154:157], v[98:113]
	v_mfma_f32_32x32x16_bf16 v[66:81], v[182:185], v[158:161], v[66:81]
	v_mfma_f32_32x32x16_bf16 v[34:49], v[178:181], v[158:161], v[34:49]
	v_mfma_f32_32x32x16_bf16 v[82:97], v[174:177], v[154:157], v[82:97]
	v_mfma_f32_32x32x16_bf16 v[50:65], v[170:173], v[154:157], v[50:65]
	v_mfma_f32_32x32x16_bf16 v[18:33], v[174:177], v[158:161], v[18:33]
	s_add_i32 s10, s47, 0x6000
	s_cmpk_lg_u32 s47, 0xc000
	s_cselect_b32 s47, s10, 0
	v_mfma_f32_32x32x16_bf16 v[2:17], v[170:173], v[158:161], v[2:17]
	s_add_i32 s11, s47, 16
	s_waitcnt vmcnt(0) lgkmcnt(0)
	s_barrier
	v_add_u32_e32 v158, s11, v219
	v_add_u32_e32 v170, s11, v218
	v_add_u32_e32 v158, v158, v0
	v_add_u32_e32 v170, v170, v0
	ds_read_b128 v[154:157], v158
	ds_read_b128 v[182:185], v170 offset:8192
	ds_read_b128 v[178:181], v170 offset:10240
	ds_read_b128 v[158:161], v158 offset:2048
	ds_read_b128 v[174:177], v170 offset:12288
	ds_read_b128 v[170:173], v170 offset:14336
	v_mfma_f32_32x32x16_bf16 v[114:129], v[162:165], v[138:141], v[114:129]
	v_mfma_f32_32x32x16_bf16 v[98:113], v[166:169], v[138:141], v[98:113]
	v_mfma_f32_32x32x16_bf16 v[66:81], v[162:165], v[142:145], v[66:81]
	v_mfma_f32_32x32x16_bf16 v[34:49], v[166:169], v[142:145], v[34:49]
	v_mfma_f32_32x32x16_bf16 v[82:97], v[146:149], v[138:141], v[82:97]
	v_mfma_f32_32x32x16_bf16 v[50:65], v[150:153], v[138:141], v[50:65]
	v_mfma_f32_32x32x16_bf16 v[18:33], v[146:149], v[142:145], v[18:33]
	v_mfma_f32_32x32x16_bf16 v[2:17], v[150:153], v[142:145], v[2:17]
	s_add_i32 s11, s47, 16
	v_add_u32_e32 v142, s11, v219
	v_add_u32_e32 v150, s11, v218
	v_add_u32_e32 v142, v142, v220
	v_add_u32_e32 v150, v150, v220
	ds_read_b128 v[138:141], v142
	ds_read_b128 v[162:165], v150 offset:8192
	ds_read_b128 v[166:169], v150 offset:10240
	ds_read_b128 v[142:145], v142 offset:2048
	ds_read_b128 v[146:149], v150 offset:12288
	ds_read_b128 v[150:153], v150 offset:14336
	s_waitcnt lgkmcnt(6)
	v_mfma_f32_32x32x16_bf16 v[114:129], v[182:185], v[154:157], v[114:129]
	v_mfma_f32_32x32x16_bf16 v[98:113], v[178:181], v[154:157], v[98:113]
	v_mfma_f32_32x32x16_bf16 v[66:81], v[182:185], v[158:161], v[66:81]
	v_mfma_f32_32x32x16_bf16 v[34:49], v[178:181], v[158:161], v[34:49]
	v_mfma_f32_32x32x16_bf16 v[82:97], v[174:177], v[154:157], v[82:97]
	v_mfma_f32_32x32x16_bf16 v[50:65], v[170:173], v[154:157], v[50:65]
	v_mfma_f32_32x32x16_bf16 v[18:33], v[174:177], v[158:161], v[18:33]
	v_mfma_f32_32x32x16_bf16 v[2:17], v[170:173], v[158:161], v[2:17]
	s_waitcnt lgkmcnt(0)
	v_mfma_f32_32x32x16_bf16 v[114:129], v[162:165], v[138:141], v[114:129]
	v_mfma_f32_32x32x16_bf16 v[98:113], v[166:169], v[138:141], v[98:113]
	v_mfma_f32_32x32x16_bf16 v[66:81], v[162:165], v[142:145], v[66:81]
	v_mfma_f32_32x32x16_bf16 v[34:49], v[166:169], v[142:145], v[34:49]
	v_mfma_f32_32x32x16_bf16 v[82:97], v[146:149], v[138:141], v[82:97]
	v_mfma_f32_32x32x16_bf16 v[50:65], v[150:153], v[138:141], v[50:65]
	v_mfma_f32_32x32x16_bf16 v[18:33], v[146:149], v[142:145], v[18:33]
	v_mfma_f32_32x32x16_bf16 v[2:17], v[150:153], v[142:145], v[2:17]
	s_waitcnt lgkmcnt(0)
	s_setprio 0
	v_mul_lo_u32 v0, v197, s55
	v_add_u32_e32 v0, 16, v0
	s_nop 1
	v_cvt_pk_bf16_f32 v114, v114, v115
	v_cvt_pk_bf16_f32 v115, v116, v117
	v_lshlrev_b32_e32 v116, 3, v196
	s_lshl_b32 s10, s42, 1
	v_add3_u32 v0, v0, v116, s10
	v_cvt_pk_bf16_f32 v116, v118, v119
	v_cvt_pk_bf16_f32 v117, v120, v121
	v_cvt_pk_bf16_f32 v98, v98, v99
	v_cvt_pk_bf16_f32 v99, v100, v101
	v_cvt_pk_bf16_f32 v100, v102, v103
	v_cvt_pk_bf16_f32 v101, v104, v105
	v_cvt_pk_bf16_f32 v82, v82, v83
	v_cvt_pk_bf16_f32 v83, v84, v85
	v_cvt_pk_bf16_f32 v84, v86, v87
	v_cvt_pk_bf16_f32 v85, v88, v89
	v_cvt_pk_bf16_f32 v50, v50, v51
	v_cvt_pk_bf16_f32 v51, v52, v53
	v_cvt_pk_bf16_f32 v52, v54, v55
	v_cvt_pk_bf16_f32 v53, v56, v57
	s_waitcnt vmcnt(0)
	s_barrier
; #define GAS __attribute__((address_space(1)))
; DI unsigned pk2(float a, float b) { f32x2 v = {a, b}; bf2_t r = __builtin_convertvector(v, bf2_t); return __builtin_bit_cast(unsigned, r); }
;     ...
;   {
;     const int h = lane >> 5, cl = lane & 31;
; #pragma unroll
;     for (int i = 0; i < 2; ++i)
; #pragma unroll
;       for (int j = 0; j < 4; ++j)
; #pragma unroll
;         for (int g = 0; g < 4; ++g) {
;           u32x2 w; w.x = pk2(acc[i][j][4 * g], acc[i][j][4 * g + 1]); w.y = pk2(acc[i][j][4 * g + 2], acc[i][j][4 * g + 3]);
;           *(u32x2*)(smem + (wr * 64 + i * 32 + cl) * 528 + (wc * 128 + j * 32 + 8 * g + 4 * h) * 2) = w;
;         }
;   }
;   __syncthreads();
;   int tid2 = tid; asm volatile("" : "+v"(tid2));
;   if (EPI == 0) {
; #pragma unroll
;     for (int i = 0; i < 16; ++i) {
;       const int id = tid2 + 256 * i, r = id >> 5, c8 = (id & 31) * 8;
;       const u32x4 v = *(const u32x4*)(smem + r * 528 + c8 * 2);
;       *(GAS u32x4*)(ea.out + (size_t)(m0 + r) * ea.ldo + n0 + c8) = v;
;     }
	ds_write2_b64 v0, v[114:115], v[116:117] offset1:2
	v_cvt_pk_bf16_f32 v114, v122, v123
	v_cvt_pk_bf16_f32 v115, v124, v125
	v_cvt_pk_bf16_f32 v116, v126, v127
	v_cvt_pk_bf16_f32 v117, v128, v129
	ds_write2_b64 v0, v[98:99], v[100:101] offset0:8 offset1:10
	v_cvt_pk_bf16_f32 v98, v106, v107
	v_cvt_pk_bf16_f32 v99, v108, v109
	v_cvt_pk_bf16_f32 v100, v110, v111
	v_cvt_pk_bf16_f32 v101, v112, v113
	ds_write2_b64 v0, v[82:83], v[84:85] offset0:16 offset1:18
	v_cvt_pk_bf16_f32 v82, v90, v91
	v_cvt_pk_bf16_f32 v83, v92, v93
	v_cvt_pk_bf16_f32 v84, v94, v95
	v_cvt_pk_bf16_f32 v85, v96, v97
	ds_write2_b64 v0, v[50:51], v[52:53] offset0:24 offset1:26
	v_cvt_pk_bf16_f32 v50, v58, v59
	v_cvt_pk_bf16_f32 v51, v60, v61
	v_cvt_pk_bf16_f32 v52, v62, v63
	v_cvt_pk_bf16_f32 v53, v64, v65
	ds_write2_b64 v0, v[114:115], v[116:117] offset0:4 offset1:6
	ds_write2_b64 v0, v[98:99], v[100:101] offset0:12 offset1:14
	ds_write2_b64 v0, v[82:83], v[84:85] offset0:20 offset1:22
	ds_write2_b64 v0, v[50:51], v[52:53] offset0:28 offset1:30
	v_cvt_pk_bf16_f32 v50, v66, v67
	v_cvt_pk_bf16_f32 v51, v68, v69
	v_cvt_pk_bf16_f32 v52, v70, v71
	v_cvt_pk_bf16_f32 v53, v72, v73
	v_add_u32_e32 v0, 0x4000, v0
	v_cvt_pk_bf16_f32 v34, v34, v35
	v_cvt_pk_bf16_f32 v35, v36, v37
	v_cvt_pk_bf16_f32 v36, v38, v39
	v_cvt_pk_bf16_f32 v37, v40, v41
	v_cvt_pk_bf16_f32 v18, v18, v19
	v_cvt_pk_bf16_f32 v19, v20, v21
	v_cvt_pk_bf16_f32 v20, v22, v23
	v_cvt_pk_bf16_f32 v21, v24, v25
	v_cvt_pk_bf16_f32 v2, v2, v3
	v_cvt_pk_bf16_f32 v3, v4, v5
	v_cvt_pk_bf16_f32 v4, v6, v7
	v_cvt_pk_bf16_f32 v5, v8, v9
	ds_write2_b64 v0, v[50:51], v[52:53] offset0:64 offset1:66
	v_cvt_pk_bf16_f32 v50, v74, v75
	v_cvt_pk_bf16_f32 v51, v76, v77
	v_cvt_pk_bf16_f32 v52, v78, v79
	v_cvt_pk_bf16_f32 v53, v80, v81
	ds_write2_b64 v0, v[34:35], v[36:37] offset0:72 offset1:74
	v_cvt_pk_bf16_f32 v34, v42, v43
	v_cvt_pk_bf16_f32 v35, v44, v45
	v_cvt_pk_bf16_f32 v36, v46, v47
	v_cvt_pk_bf16_f32 v37, v48, v49
	ds_write2_b64 v0, v[18:19], v[20:21] offset0:80 offset1:82
	v_cvt_pk_bf16_f32 v18, v26, v27
	v_cvt_pk_bf16_f32 v19, v28, v29
	v_cvt_pk_bf16_f32 v20, v30, v31
	v_cvt_pk_bf16_f32 v21, v32, v33
	ds_write2_b64 v0, v[2:3], v[4:5] offset0:88 offset1:90
	v_cvt_pk_bf16_f32 v2, v10, v11
	v_cvt_pk_bf16_f32 v3, v12, v13
	v_cvt_pk_bf16_f32 v4, v14, v15
	v_cvt_pk_bf16_f32 v5, v16, v17
	s_lshl_b64 s[12:13], s[12:13], 1
	ds_write2_b64 v0, v[50:51], v[52:53] offset0:68 offset1:70
	ds_write2_b64 v0, v[34:35], v[36:37] offset0:76 offset1:78
	ds_write2_b64 v0, v[18:19], v[20:21] offset0:84 offset1:86
	ds_write2_b64 v0, v[2:3], v[4:5] offset0:92 offset1:94
	s_waitcnt vmcnt(0) lgkmcnt(0)
	s_barrier
	s_add_u32 s12, s16, s12
	v_lshlrev_b32_e32 v0, 4, v189
	v_and_b32_e32 v0, 0x1f0, v0
	s_addc_u32 s13, s17, s13
	v_add_u32_e32 v10, 16, v0
	v_lshl_add_u64 v[12:13], s[12:13], 0, v[0:1]
	v_ashrrev_i32_e32 v0, 5, v189
	v_mad_u64_u32 v[2:3], s[12:13], v0, s55, v[10:11]
	ds_read_b128 v[2:5], v2
	v_add_u32_e32 v6, s41, v0
	v_ashrrev_i32_e32 v7, 31, v6
	v_add_u32_e32 v0, 0x100, v189
	v_lshlrev_b64 v[6:7], 11, v[6:7]
	v_ashrrev_i32_e32 v0, 5, v0
	v_lshl_add_u64 v[14:15], v[12:13], 0, v[6:7]
	v_mad_u64_u32 v[6:7], s[12:13], v0, s55, v[10:11]
	ds_read_b128 v[6:9], v6
	s_waitcnt lgkmcnt(1)
	global_store_dwordx4 v[14:15], v[2:5], off
	v_readlane_b32 s44, v250, 17
	s_nop 0
	v_add_u32_e32 v2, s41, v0
	v_ashrrev_i32_e32 v3, 31, v2
	v_lshlrev_b64 v[2:3], 11, v[2:3]
	v_add_u32_e32 v0, 0x200, v189
	v_lshl_add_u64 v[2:3], v[12:13], 0, v[2:3]
	v_ashrrev_i32_e32 v0, 5, v0
	s_waitcnt lgkmcnt(0)
	global_store_dwordx4 v[2:3], v[6:9], off
	v_mad_u64_u32 v[2:3], s[12:13], v0, s55, v[10:11]
	ds_read_b128 v[2:5], v2
	v_add_u32_e32 v6, s41, v0
	v_ashrrev_i32_e32 v7, 31, v6
	v_add_u32_e32 v0, 0x300, v189
	v_lshlrev_b64 v[6:7], 11, v[6:7]
	v_ashrrev_i32_e32 v0, 5, v0
	v_lshl_add_u64 v[14:15], v[12:13], 0, v[6:7]
	v_mad_u64_u32 v[6:7], s[12:13], v0, s55, v[10:11]
	ds_read_b128 v[6:9], v6
	s_waitcnt lgkmcnt(1)
	global_store_dwordx4 v[14:15], v[2:5], off
	s_nop 1
	v_add_u32_e32 v2, s41, v0
	v_ashrrev_i32_e32 v3, 31, v2
	v_lshlrev_b64 v[2:3], 11, v[2:3]
	v_add_u32_e32 v0, 0x400, v189
	v_lshl_add_u64 v[2:3], v[12:13], 0, v[2:3]
	v_ashrrev_i32_e32 v0, 5, v0
	s_waitcnt lgkmcnt(0)
	global_store_dwordx4 v[2:3], v[6:9], off
	v_mad_u64_u32 v[2:3], s[12:13], v0, s55, v[10:11]
	ds_read_b128 v[2:5], v2
	v_add_u32_e32 v6, s41, v0
	v_ashrrev_i32_e32 v7, 31, v6
	v_add_u32_e32 v0, 0x500, v189
	v_lshlrev_b64 v[6:7], 11, v[6:7]
	v_ashrrev_i32_e32 v0, 5, v0
	v_lshl_add_u64 v[14:15], v[12:13], 0, v[6:7]
	v_mad_u64_u32 v[6:7], s[12:13], v0, s55, v[10:11]
	ds_read_b128 v[6:9], v6
	s_waitcnt lgkmcnt(1)
	global_store_dwordx4 v[14:15], v[2:5], off
	s_nop 1
	v_add_u32_e32 v2, s41, v0
	v_ashrrev_i32_e32 v3, 31, v2
	v_lshlrev_b64 v[2:3], 11, v[2:3]
	v_add_u32_e32 v0, 0x600, v189
	v_lshl_add_u64 v[2:3], v[12:13], 0, v[2:3]
	v_ashrrev_i32_e32 v0, 5, v0
	s_waitcnt lgkmcnt(0)
	global_store_dwordx4 v[2:3], v[6:9], off
	v_mad_u64_u32 v[2:3], s[12:13], v0, s55, v[10:11]
	ds_read_b128 v[2:5], v2
	v_add_u32_e32 v6, s41, v0
	v_ashrrev_i32_e32 v7, 31, v6
	v_add_u32_e32 v0, 0x700, v189
	v_lshlrev_b64 v[6:7], 11, v[6:7]
	v_ashrrev_i32_e32 v0, 5, v0
	v_lshl_add_u64 v[14:15], v[12:13], 0, v[6:7]
	v_mad_u64_u32 v[6:7], s[12:13], v0, s55, v[10:11]
	ds_read_b128 v[6:9], v6
	s_waitcnt lgkmcnt(1)
	global_store_dwordx4 v[14:15], v[2:5], off
	s_nop 1
	v_add_u32_e32 v2, s41, v0
	v_ashrrev_i32_e32 v3, 31, v2
	v_lshlrev_b64 v[2:3], 11, v[2:3]
	v_add_u32_e32 v0, 0x800, v189
	v_lshl_add_u64 v[2:3], v[12:13], 0, v[2:3]
	v_ashrrev_i32_e32 v0, 5, v0
	s_waitcnt lgkmcnt(0)
; #define GAS __attribute__((address_space(1)))
; #define LAS __attribute__((address_space(3)))
;   int tid = tid_in; asm volatile("" : "+v"(tid));
;   const int lane = tid & 63, wid = __builtin_amdgcn_readfirstlane(tid >> 6), wr = wid >> 1, wc = wid & 1;
;   const int m0 = mt * 128, n0 = nt * 256;
;   const int r = lane & 31, h = lane >> 5, key = (r >> 2) & 3;
;   constexpr int STG = 24576;
;   const int rowl = lane >> 2, cch = (lane & 3) ^ ((lane >> 4) & 3);
;   const unsigned voffA = (unsigned)(rowl * lda * 2 + cch * 16), voffB = (unsigned)(rowl * K * 2 + cch * 16);
;   const char* Abase = (const char*)(A + (size_t)m0 * lda) + (size_t)(wid * 2) * 32 * lda;
;   const char* Bbase = (const char*)(Bt + (size_t)n0 * K) + (size_t)(wid * 4) * 32 * K;
;   const size_t ablk = (size_t)32 * lda, bblk = (size_t)32 * K;
;   LAS char* lds = (LAS char*)smem;
;   LAS char* ldsA = lds + (wid * 2) * 1024;
;   LAS char* ldsB = lds + 8192 + (wid * 4) * 1024;
;     ...
;   const int x0 = ((0 + h) ^ key) * 16, x1 = ((2 + h) ^ key) * 16;
;   const int a_rd = (wr * 64 + r) * 64, b_rd = 8192 + (wc * 128 + r) * 64;
;   f32x16 acc[2][4];
; #pragma unroll
;   for (int i = 0; i < 2; ++i)
; #pragma unroll
;     for (int j = 0; j < 4; ++j)
; #pragma unroll
;       for (int e = 0; e < 16; ++e) acc[i][j][e] = 0.f;
;   const int nk = K >> 5;
;   DMA_STEP_(0, 0);
;   DMA_STEP_(1, STG);
;   asm volatile("s_waitcnt vmcnt(6)" ::: "memory");
;   __builtin_amdgcn_s_barrier();
;     ...
;     for (int i = 0; i < 16; ++i) {
;       const int id = tid2 + 256 * i, r = id >> 5, c8 = (id & 31) * 8;
;       const u32x4 v = *(const u32x4*)(smem + r * 528 + c8 * 2);
;       *(GAS u32x4*)(ea.out + (size_t)(m0 + r) * ea.ldo + n0 + c8) = v;
;     }
	global_store_dwordx4 v[2:3], v[6:9], off
	v_mad_u64_u32 v[2:3], s[12:13], v0, s55, v[10:11]
	ds_read_b128 v[2:5], v2
	v_add_u32_e32 v6, s41, v0
	v_ashrrev_i32_e32 v7, 31, v6
	v_add_u32_e32 v0, 0x900, v189
	v_lshlrev_b64 v[6:7], 11, v[6:7]
	v_ashrrev_i32_e32 v0, 5, v0
	v_lshl_add_u64 v[14:15], v[12:13], 0, v[6:7]
	v_mad_u64_u32 v[6:7], s[12:13], v0, s55, v[10:11]
	ds_read_b128 v[6:9], v6
	s_waitcnt lgkmcnt(1)
	global_store_dwordx4 v[14:15], v[2:5], off
	s_nop 1
	v_add_u32_e32 v2, s41, v0
	v_ashrrev_i32_e32 v3, 31, v2
	v_lshlrev_b64 v[2:3], 11, v[2:3]
	v_add_u32_e32 v0, 0xa00, v189
	v_lshl_add_u64 v[2:3], v[12:13], 0, v[2:3]
	v_ashrrev_i32_e32 v0, 5, v0
	s_waitcnt lgkmcnt(0)
	global_store_dwordx4 v[2:3], v[6:9], off
	v_mad_u64_u32 v[2:3], s[12:13], v0, s55, v[10:11]
	ds_read_b128 v[2:5], v2
	v_add_u32_e32 v6, s41, v0
	v_ashrrev_i32_e32 v7, 31, v6
	v_add_u32_e32 v0, 0xb00, v189
	v_lshlrev_b64 v[6:7], 11, v[6:7]
	v_ashrrev_i32_e32 v0, 5, v0
	v_lshl_add_u64 v[14:15], v[12:13], 0, v[6:7]
	v_mad_u64_u32 v[6:7], s[12:13], v0, s55, v[10:11]
	ds_read_b128 v[6:9], v6
	s_waitcnt lgkmcnt(1)
	global_store_dwordx4 v[14:15], v[2:5], off
	s_nop 1
	v_add_u32_e32 v2, s41, v0
	v_ashrrev_i32_e32 v3, 31, v2
	v_lshlrev_b64 v[2:3], 11, v[2:3]
	v_add_u32_e32 v0, 0xc00, v189
	v_lshl_add_u64 v[2:3], v[12:13], 0, v[2:3]
	v_ashrrev_i32_e32 v0, 5, v0
	s_waitcnt lgkmcnt(0)
	global_store_dwordx4 v[2:3], v[6:9], off
	v_mad_u64_u32 v[2:3], s[12:13], v0, s55, v[10:11]
	ds_read_b128 v[2:5], v2
	v_add_u32_e32 v6, s41, v0
	v_ashrrev_i32_e32 v7, 31, v6
	v_add_u32_e32 v0, 0xd00, v189
	v_lshlrev_b64 v[6:7], 11, v[6:7]
	v_ashrrev_i32_e32 v0, 5, v0
	v_lshl_add_u64 v[14:15], v[12:13], 0, v[6:7]
	v_mad_u64_u32 v[6:7], s[12:13], v0, s55, v[10:11]
	ds_read_b128 v[6:9], v6
	s_waitcnt lgkmcnt(1)
	global_store_dwordx4 v[14:15], v[2:5], off
	s_nop 1
	v_add_u32_e32 v2, s41, v0
	v_ashrrev_i32_e32 v3, 31, v2
	v_lshlrev_b64 v[2:3], 11, v[2:3]
	v_add_u32_e32 v0, 0xe00, v189
	v_lshl_add_u64 v[2:3], v[12:13], 0, v[2:3]
	v_ashrrev_i32_e32 v0, 5, v0
	s_waitcnt lgkmcnt(0)
	global_store_dwordx4 v[2:3], v[6:9], off
	v_mad_u64_u32 v[2:3], s[12:13], v0, s55, v[10:11]
	ds_read_b128 v[2:5], v2
	v_add_u32_e32 v6, s41, v0
	v_ashrrev_i32_e32 v7, 31, v6
	v_add_u32_e32 v0, 0xf00, v189
	v_lshlrev_b64 v[6:7], 11, v[6:7]
	v_ashrrev_i32_e32 v0, 5, v0
	v_lshl_add_u64 v[14:15], v[12:13], 0, v[6:7]
	v_mad_u64_u32 v[6:7], s[12:13], v0, s55, v[10:11]
	ds_read_b128 v[6:9], v6
	s_waitcnt lgkmcnt(1)
	global_store_dwordx4 v[14:15], v[2:5], off
	s_mov_b64 s[12:13], 0
	s_nop 0
	v_add_u32_e32 v2, s41, v0
	v_ashrrev_i32_e32 v3, 31, v2
	v_lshlrev_b64 v[2:3], 11, v[2:3]
	v_lshl_add_u64 v[2:3], v[12:13], 0, v[2:3]
	s_waitcnt lgkmcnt(0)
	global_store_dwordx4 v[2:3], v[6:9], off
	s_barrier
.LBB0_150:
	s_and_b64 vcc, exec, s[12:13]
	s_cbranch_vccz .LBB0_145
	s_mul_hi_i32 s10, s40, 0x2aaaaaab
	s_lshr_b32 s11, s10, 31
	s_ashr_i32 s10, s10, 2
	s_add_i32 s10, s10, s11
	v_readlane_b32 s12, v252, 18
	v_mov_b32_e32 v189, v188
	s_mul_i32 s11, s10, 0xffffffe8
	s_lshl_b32 s10, s10, s12
	v_readlane_b32 s12, v252, 41
	s_add_i32 s10, s10, s12
	v_readfirstlane_b32 s43, v189
	s_ashr_i32 s45, s43, 6
	s_lshl_b32 s12, s40, 7
	s_add_i32 s11, s11, s40
	s_lshl_b32 s10, s10, 10
	s_and_b32 s12, s12, 0x380
	s_lshl_b32 s44, s45, 2
	s_ashr_i32 s43, s43, 1
	s_or_b32 s41, s10, s12
	s_lshl_b32 s10, s11, 5
	v_and_b32_e32 v0, 31, v189
	s_mov_b32 s59, 0
	s_lshl_b32 s44, s45, 12
	s_andn2_b32 s43, s43, 63
	s_and_b32 s12, s10, 0xffffff00
	s_add_i32 s44, s44, 16
	v_or_b32_e32 v197, s43, v0
	s_lshl_b32 s43, s45, 7
	s_lshl_b32 s10, s45, 1
	s_ashr_i32 s13, s12, 31
	s_add_i32 s60, s44, 0x2000
	s_and_b32 s43, s43, 0x80
	s_mul_i32 s57, s41, 0x1200
	s_mul_hi_i32 s56, s41, 0x1200
	s_add_u32 s57, s22, s57
	s_mul_i32 s11, s45, 0x24000
	s_addc_u32 s58, s23, s56
	s_mul_hi_i32 s10, s10, 0x12000
	s_add_u32 s56, s57, s11
	s_addc_u32 s57, s58, s10
	s_mul_i32 s11, s12, 64
	s_mov_b32 s10, 0
	s_add_u32 s11, s28, s11
	s_mul_i32 s47, s45, 0x1000
	s_addc_u32 s10, s29, s10
	v_bfe_u32 v2, v189, 2, 4
	v_lshlrev_b32_e32 v3, 4, v189
	s_add_u32 s58, s11, s47
	v_bitop3_b32 v5, v3, 48, v189 bitop3:0x48
	v_or_b32_e32 v3, s43, v0
	v_mul_u32_u24_e32 v0, 0x1200, v2
	s_addc_u32 s59, s10, s59
	s_lshl_b32 s10, s45, 11
	v_or_b32_e32 v0, v0, v5
	s_sub_i32 s45, s44, s10
	v_mul_u32_u24_e32 v6, 0x300, v2
	v_lshl_or_b32 v10, v2, 6, v5
	v_mov_b32_e32 v11, 0
	v_lshl_add_u64 v[192:193], s[56:57], 0, v[0:1]
	s_mov_b32 m0, s45
	s_mov_b64 s[10:11], 0x12000
	v_lshlrev_b32_e32 v218, 6, v3
	global_load_lds_dwordx4 v0, s[56:57]
	v_lshl_add_u64 v[2:3], v[192:193], 0, s[10:11]
	s_add_i32 m0, s45, 0x400
	v_or_b32_e32 v0, v6, v5
	global_load_lds_dwordx4 v[2:3], off
	v_lshl_add_u64 v[194:195], s[58:59], 0, v[10:11]
	s_mov_b32 m0, s60
	s_mov_b64 s[56:57], 0x3000
	global_load_lds_dwordx4 v[194:195], off
	global_load_lds_dwordx4 v[194:195], off offset:1024
	global_load_lds_dwordx4 v[194:195], off offset:2048
	global_load_lds_dwordx4 v[194:195], off offset:3072
	s_mov_b64 s[10:11], 0x6000
	s_mov_b64 s[56:57], 0x9000
	s_mov_b64 s[10:11], 0x12040
	s_add_i32 m0, s45, 0x6000
	v_lshl_add_u64 v[2:3], v[192:193], 0, 64
	global_load_lds_dwordx4 v[2:3], off
	v_lshl_add_u64 v[2:3], v[192:193], 0, s[10:11]
	s_add_i32 m0, s45, 0x6400
	s_mov_b64 s[56:57], 0x3040
	global_load_lds_dwordx4 v[2:3], off
	s_add_i32 m0, s44, 0x8000
	s_mov_b32 s100, 0xc000
	v_lshl_add_u64 v[2:3], v[194:195], 0, s[100:101]
	global_load_lds_dwordx4 v[2:3], off
	global_load_lds_dwordx4 v[2:3], off offset:1024
	global_load_lds_dwordx4 v[2:3], off offset:2048
	global_load_lds_dwordx4 v[2:3], off offset:3072
	s_mov_b64 s[10:11], 0x6040
	s_mov_b64 s[56:57], 0x9040
	v_bfe_u32 v196, v189, 5, 1
	v_bfe_u32 v5, v189, 2, 2
	v_lshrrev_b32_e32 v4, 2, v189
	s_lshl_b32 s100, s100, 1
	v_lshl_add_u64 v[194:195], v[194:195], 0, s[100:101]
	s_waitcnt vmcnt(6)
	s_barrier
; #define LAS __attribute__((address_space(3)))
; DI f32x16 mfma32(bf16x8 a, bf16x8 b, f32x16 c) { return __builtin_amdgcn_mfma_f32_32x32x16_bf16(a, b, c, 0, 0, 0); }
;     ...
;   f32x16 acc[2][4];
; #pragma unroll
;   for (int i = 0; i < 2; ++i)
; #pragma unroll
;     for (int j = 0; j < 4; ++j)
; #pragma unroll
;       for (int e = 0; e < 16; ++e) acc[i][j][e] = 0.f;
;   const int nk = K >> 5;
;   DMA_STEP_(0, 0);
;   DMA_STEP_(1, STG);
;   asm volatile("s_waitcnt vmcnt(6)" ::: "memory");
;   __builtin_amdgcn_s_barrier();
;   asm volatile("" ::: "memory");
;   int s0 = 0, s2 = 2 * STG;
;   for (int kt = 0; kt < nk; ++kt) {
;     const int kn = (kt + 2 < nk) ? (kt + 2) : (nk - 1);
;     const LAS char* cur = lds + s0;
;     bf16x8 af[2][2], bfr[2][4];
; #pragma unroll
;     for (int kk = 0; kk < 2; ++kk) {
;       const int xo = kk ? x1 : x0;
;       af[kk][0] = *(const LAS bf16x8*)(cur + a_rd + xo);
;       bfr[kk][0] = *(const LAS bf16x8*)(cur + b_rd + xo);
;       bfr[kk][1] = *(const LAS bf16x8*)(cur + b_rd + 2048 + xo);
;       af[kk][1] = *(const LAS bf16x8*)(cur + a_rd + 2048 + xo);
;       bfr[kk][2] = *(const LAS bf16x8*)(cur + b_rd + 4096 + xo);
;       bfr[kk][3] = *(const LAS bf16x8*)(cur + b_rd + 6144 + xo);
;     }
;     DMA_STEP_(kn, s2);
; #pragma unroll
;     for (int kk = 0; kk < 2; ++kk) {
;       acc[0][0] = mfma32(bfr[kk][0], af[kk][0], acc[0][0]); acc[0][1] = mfma32(bfr[kk][1], af[kk][0], acc[0][1]);
;       acc[1][0] = mfma32(bfr[kk][0], af[kk][1], acc[1][0]); acc[1][1] = mfma32(bfr[kk][1], af[kk][1], acc[1][1]);
;       acc[0][2] = mfma32(bfr[kk][2], af[kk][0], acc[0][2]); acc[0][3] = mfma32(bfr[kk][3], af[kk][0], acc[0][3]);
;       acc[1][2] = mfma32(bfr[kk][2], af[kk][1], acc[1][2]); acc[1][3] = mfma32(bfr[kk][3], af[kk][1], acc[1][3]);
;     }
;     __builtin_amdgcn_sched_group_barrier(0x100, 12, 0);
;     __builtin_amdgcn_sched_group_barrier(0x010, 6, 0);
;     __builtin_amdgcn_sched_group_barrier(0x008, 16, 0);
;     asm volatile("s_waitcnt vmcnt(6) lgkmcnt(0)" ::: "memory");
;     __builtin_amdgcn_s_barrier();
;     asm volatile("" ::: "memory");
;     s0 = (s0 == 2 * STG) ? 0 : s0 + STG;
;     s2 = (s2 == 2 * STG) ? 0 : s2 + STG;
;   }
	v_bitop3_b32 v2, v196, v5, 2 bitop3:0x36
	v_bitop3_b32 v0, v196, v4, 3 bitop3:0x78
	v_lshlrev_b32_e32 v220, 4, v2
	v_mov_b32_e32 v2, 0
	s_mov_b32 s42, 1
	s_mov_b32 s46, 0xc000
	v_lshlrev_b32_e32 v219, 6, v197
	v_lshlrev_b32_e32 v0, 4, v0
	s_mov_b32 s47, 0
	v_mov_b32_e32 v3, v2
	v_mov_b32_e32 v4, v2
	v_mov_b32_e32 v5, v2
	v_mov_b32_e32 v6, v2
	v_mov_b32_e32 v7, v2
	v_mov_b32_e32 v8, v2
	v_mov_b32_e32 v9, v2
	v_mov_b32_e32 v10, v2
	v_mov_b32_e32 v11, v2
	v_mov_b32_e32 v12, v2
	v_mov_b32_e32 v13, v2
	v_mov_b32_e32 v14, v2
	v_mov_b32_e32 v15, v2
	v_mov_b32_e32 v16, v2
	v_mov_b32_e32 v17, v2
	v_mov_b32_e32 v18, v2
	v_mov_b32_e32 v19, v2
	v_mov_b32_e32 v20, v2
	v_mov_b32_e32 v21, v2
	v_mov_b32_e32 v22, v2
	v_mov_b32_e32 v23, v2
	v_mov_b32_e32 v24, v2
	v_mov_b32_e32 v25, v2
	v_mov_b32_e32 v26, v2
	v_mov_b32_e32 v27, v2
	v_mov_b32_e32 v28, v2
	v_mov_b32_e32 v29, v2
	v_mov_b32_e32 v30, v2
	v_mov_b32_e32 v31, v2
	v_mov_b32_e32 v32, v2
	v_mov_b32_e32 v33, v2
	v_mov_b32_e32 v50, v2
	v_mov_b32_e32 v51, v2
	v_mov_b32_e32 v52, v2
	v_mov_b32_e32 v53, v2
	v_mov_b32_e32 v54, v2
	v_mov_b32_e32 v55, v2
	v_mov_b32_e32 v56, v2
	v_mov_b32_e32 v57, v2
	v_mov_b32_e32 v58, v2
	v_mov_b32_e32 v59, v2
	v_mov_b32_e32 v60, v2
	v_mov_b32_e32 v61, v2
	v_mov_b32_e32 v62, v2
	v_mov_b32_e32 v63, v2
	v_mov_b32_e32 v64, v2
	v_mov_b32_e32 v65, v2
	v_mov_b32_e32 v82, v2
	v_mov_b32_e32 v83, v2
	v_mov_b32_e32 v84, v2
	v_mov_b32_e32 v85, v2
	v_mov_b32_e32 v86, v2
	v_mov_b32_e32 v87, v2
	v_mov_b32_e32 v88, v2
	v_mov_b32_e32 v89, v2
	v_mov_b32_e32 v90, v2
	v_mov_b32_e32 v91, v2
	v_mov_b32_e32 v92, v2
	v_mov_b32_e32 v93, v2
	v_mov_b32_e32 v94, v2
	v_mov_b32_e32 v95, v2
	v_mov_b32_e32 v96, v2
	v_mov_b32_e32 v97, v2
	v_mov_b32_e32 v34, v2
	v_mov_b32_e32 v35, v2
	v_mov_b32_e32 v36, v2
	v_mov_b32_e32 v37, v2
	v_mov_b32_e32 v38, v2
	v_mov_b32_e32 v39, v2
	v_mov_b32_e32 v40, v2
	v_mov_b32_e32 v41, v2
	v_mov_b32_e32 v42, v2
	v_mov_b32_e32 v43, v2
	v_mov_b32_e32 v44, v2
	v_mov_b32_e32 v45, v2
	v_mov_b32_e32 v46, v2
	v_mov_b32_e32 v47, v2
	v_mov_b32_e32 v48, v2
	v_mov_b32_e32 v49, v2
	v_mov_b32_e32 v66, v2
	v_mov_b32_e32 v67, v2
	v_mov_b32_e32 v68, v2
	v_mov_b32_e32 v69, v2
	v_mov_b32_e32 v70, v2
	v_mov_b32_e32 v71, v2
	v_mov_b32_e32 v72, v2
	v_mov_b32_e32 v73, v2
	v_mov_b32_e32 v74, v2
	v_mov_b32_e32 v75, v2
	v_mov_b32_e32 v76, v2
	v_mov_b32_e32 v77, v2
	v_mov_b32_e32 v78, v2
	v_mov_b32_e32 v79, v2
	v_mov_b32_e32 v80, v2
	v_mov_b32_e32 v81, v2
	v_mov_b32_e32 v98, v2
	v_mov_b32_e32 v99, v2
	v_mov_b32_e32 v100, v2
	v_mov_b32_e32 v101, v2
	v_mov_b32_e32 v102, v2
	v_mov_b32_e32 v103, v2
	v_mov_b32_e32 v104, v2
	v_mov_b32_e32 v105, v2
	v_mov_b32_e32 v106, v2
	v_mov_b32_e32 v107, v2
	v_mov_b32_e32 v108, v2
	v_mov_b32_e32 v109, v2
	v_mov_b32_e32 v110, v2
	v_mov_b32_e32 v111, v2
	v_mov_b32_e32 v112, v2
	v_mov_b32_e32 v113, v2
	v_mov_b32_e32 v114, v2
	v_mov_b32_e32 v115, v2
	v_mov_b32_e32 v116, v2
	v_mov_b32_e32 v117, v2
	v_mov_b32_e32 v118, v2
	v_mov_b32_e32 v119, v2
	v_mov_b32_e32 v120, v2
	v_mov_b32_e32 v121, v2
	v_mov_b32_e32 v122, v2
	v_mov_b32_e32 v123, v2
	v_mov_b32_e32 v124, v2
	v_mov_b32_e32 v125, v2
	v_mov_b32_e32 v126, v2
	v_mov_b32_e32 v127, v2
	v_mov_b32_e32 v128, v2
	v_mov_b32_e32 v129, v2
	s_mov_b64 s[56:57], 0x3080
	s_mov_b64 s[58:59], 0x9080
	v_add_u32_e32 v162, 16, v219
	v_add_u32_e32 v170, 16, v218
	v_add_u32_e32 v162, v162, v0
	v_add_u32_e32 v170, v170, v0
	ds_read_b128 v[158:161], v162
	ds_read_b128 v[182:185], v170 offset:8192
	ds_read_b128 v[178:181], v170 offset:10240
	ds_read_b128 v[162:165], v162 offset:2048
	ds_read_b128 v[174:177], v170 offset:12288
	ds_read_b128 v[170:173], v170 offset:14336
	s_setprio 1
.LBB0_152:
	s_add_i32 s11, s47, 16
	s_add_i32 s10, s42, -1
	v_add_u32_e32 v142, s11, v219
	v_add_u32_e32 v150, s11, v218
	s_min_u32 s10, s10, 9
	v_add_u32_e32 v142, v142, v220
	v_add_u32_e32 v150, v150, v220
	s_lshl_b32 s70, s10, 6
	ds_read_b128 v[138:141], v142
	ds_read_b128 v[166:169], v150 offset:8192
	ds_read_b128 v[154:157], v150 offset:10240
	ds_read_b128 v[142:145], v142 offset:2048
	ds_read_b128 v[146:149], v150 offset:12288
	ds_read_b128 v[150:153], v150 offset:14336
	v_lshl_add_u64 v[222:223], v[192:193], 0, s[70:71]
	s_add_i32 s10, s45, s46
	v_lshl_add_u64 v[224:225], v[222:223], 0, s[24:25]
	s_mov_b32 m0, s10
	v_lshl_add_u64 v[222:223], v[222:223], 0, s[36:37]
	s_mul_i32 s100, s70, 0x300
	s_waitcnt lgkmcnt(6)
	v_mfma_f32_32x32x16_bf16 v[114:129], v[182:185], v[158:161], v[114:129]
	global_load_lds_dwordx4 v[224:225], off
	s_add_i32 m0, s10, 0x400
	v_mfma_f32_32x32x16_bf16 v[98:113], v[178:181], v[158:161], v[98:113]
	global_load_lds_dwordx4 v[222:223], off
	v_lshl_add_u64 v[224:225], v[194:195], 0, s[100:101]
	s_add_i32 s10, s44, s46
	s_add_i32 m0, s10, 0x2000
	v_mfma_f32_32x32x16_bf16 v[66:81], v[182:185], v[162:165], v[66:81]
	global_load_lds_dwordx4 v[224:225], off
	v_mfma_f32_32x32x16_bf16 v[34:49], v[178:181], v[162:165], v[34:49]
	global_load_lds_dwordx4 v[224:225], off offset:1024
	v_mfma_f32_32x32x16_bf16 v[82:97], v[174:177], v[158:161], v[82:97]
	global_load_lds_dwordx4 v[224:225], off offset:2048
	v_mfma_f32_32x32x16_bf16 v[50:65], v[170:173], v[158:161], v[50:65]
	global_load_lds_dwordx4 v[224:225], off offset:3072
	v_mfma_f32_32x32x16_bf16 v[18:33], v[174:177], v[162:165], v[18:33]
	s_add_i32 s10, s47, 0x6000
	s_cmpk_lg_u32 s47, 0xc000
	s_cselect_b32 s47, s10, 0
	s_add_i32 s10, s46, 0x6000
	s_cmpk_lg_u32 s46, 0xc000
	s_cselect_b32 s46, s10, 0
	v_mfma_f32_32x32x16_bf16 v[2:17], v[170:173], v[162:165], v[2:17]
	s_add_i32 s11, s47, 16
	s_waitcnt vmcnt(6) lgkmcnt(0)
	s_barrier
; #define LAS __attribute__((address_space(3)))
; DI f32x16 mfma32(bf16x8 a, bf16x8 b, f32x16 c) { return __builtin_amdgcn_mfma_f32_32x32x16_bf16(a, b, c, 0, 0, 0); }
;     ...
;   for (int kt = 0; kt < nk; ++kt) {
;     const int kn = (kt + 2 < nk) ? (kt + 2) : (nk - 1);
;     const LAS char* cur = lds + s0;
;     bf16x8 af[2][2], bfr[2][4];
; #pragma unroll
;     for (int kk = 0; kk < 2; ++kk) {
;       const int xo = kk ? x1 : x0;
;       af[kk][0] = *(const LAS bf16x8*)(cur + a_rd + xo);
;       bfr[kk][0] = *(const LAS bf16x8*)(cur + b_rd + xo);
;       bfr[kk][1] = *(const LAS bf16x8*)(cur + b_rd + 2048 + xo);
;       af[kk][1] = *(const LAS bf16x8*)(cur + a_rd + 2048 + xo);
;       bfr[kk][2] = *(const LAS bf16x8*)(cur + b_rd + 4096 + xo);
;       bfr[kk][3] = *(const LAS bf16x8*)(cur + b_rd + 6144 + xo);
;     }
;     DMA_STEP_(kn, s2);
; #pragma unroll
;     for (int kk = 0; kk < 2; ++kk) {
;       acc[0][0] = mfma32(bfr[kk][0], af[kk][0], acc[0][0]); acc[0][1] = mfma32(bfr[kk][1], af[kk][0], acc[0][1]);
;       acc[1][0] = mfma32(bfr[kk][0], af[kk][1], acc[1][0]); acc[1][1] = mfma32(bfr[kk][1], af[kk][1], acc[1][1]);
;       acc[0][2] = mfma32(bfr[kk][2], af[kk][0], acc[0][2]); acc[0][3] = mfma32(bfr[kk][3], af[kk][0], acc[0][3]);
;       acc[1][2] = mfma32(bfr[kk][2], af[kk][1], acc[1][2]); acc[1][3] = mfma32(bfr[kk][3], af[kk][1], acc[1][3]);
;     }
;     __builtin_amdgcn_sched_group_barrier(0x100, 12, 0);
;     __builtin_amdgcn_sched_group_barrier(0x010, 6, 0);
;     __builtin_amdgcn_sched_group_barrier(0x008, 16, 0);
;     asm volatile("s_waitcnt vmcnt(6) lgkmcnt(0)" ::: "memory");
;     __builtin_amdgcn_s_barrier();
;     asm volatile("" ::: "memory");
;     s0 = (s0 == 2 * STG) ? 0 : s0 + STG;
;     s2 = (s2 == 2 * STG) ? 0 : s2 + STG;
;   }
	v_add_u32_e32 v162, s11, v219
	v_add_u32_e32 v170, s11, v218
	v_add_u32_e32 v162, v162, v0
	v_add_u32_e32 v170, v170, v0
	ds_read_b128 v[158:161], v162
	ds_read_b128 v[182:185], v170 offset:8192
	ds_read_b128 v[178:181], v170 offset:10240
	ds_read_b128 v[162:165], v162 offset:2048
	ds_read_b128 v[174:177], v170 offset:12288
	ds_read_b128 v[170:173], v170 offset:14336
	v_mfma_f32_32x32x16_bf16 v[114:129], v[166:169], v[138:141], v[114:129]
	v_mfma_f32_32x32x16_bf16 v[98:113], v[154:157], v[138:141], v[98:113]
	v_mfma_f32_32x32x16_bf16 v[66:81], v[166:169], v[142:145], v[66:81]
	v_mfma_f32_32x32x16_bf16 v[34:49], v[154:157], v[142:145], v[34:49]
	v_mfma_f32_32x32x16_bf16 v[82:97], v[146:149], v[138:141], v[82:97]
	v_mfma_f32_32x32x16_bf16 v[50:65], v[150:153], v[138:141], v[50:65]
	v_mfma_f32_32x32x16_bf16 v[18:33], v[146:149], v[142:145], v[18:33]
	v_mfma_f32_32x32x16_bf16 v[2:17], v[150:153], v[142:145], v[2:17]
	s_add_i32 s11, s47, 16
	s_mov_b32 s10, s42
	v_add_u32_e32 v142, s11, v219
	v_add_u32_e32 v150, s11, v218
	s_min_u32 s10, s10, 9
	v_add_u32_e32 v142, v142, v220
	v_add_u32_e32 v150, v150, v220
	s_lshl_b32 s70, s10, 6
	ds_read_b128 v[138:141], v142
	ds_read_b128 v[166:169], v150 offset:8192
	ds_read_b128 v[154:157], v150 offset:10240
	ds_read_b128 v[142:145], v142 offset:2048
	ds_read_b128 v[146:149], v150 offset:12288
	ds_read_b128 v[150:153], v150 offset:14336
	v_lshl_add_u64 v[222:223], v[192:193], 0, s[70:71]
	s_add_i32 s10, s45, s46
	v_lshl_add_u64 v[224:225], v[222:223], 0, s[24:25]
	s_mov_b32 m0, s10
	v_lshl_add_u64 v[222:223], v[222:223], 0, s[36:37]
	s_mul_i32 s100, s70, 0x300
	s_waitcnt lgkmcnt(6)
	v_mfma_f32_32x32x16_bf16 v[114:129], v[182:185], v[158:161], v[114:129]
	global_load_lds_dwordx4 v[224:225], off
	s_add_i32 m0, s10, 0x400
	v_mfma_f32_32x32x16_bf16 v[98:113], v[178:181], v[158:161], v[98:113]
	global_load_lds_dwordx4 v[222:223], off
	v_lshl_add_u64 v[224:225], v[194:195], 0, s[100:101]
	s_add_i32 s10, s44, s46
	s_add_i32 m0, s10, 0x2000
	v_mfma_f32_32x32x16_bf16 v[66:81], v[182:185], v[162:165], v[66:81]
	global_load_lds_dwordx4 v[224:225], off
	v_mfma_f32_32x32x16_bf16 v[34:49], v[178:181], v[162:165], v[34:49]
	global_load_lds_dwordx4 v[224:225], off offset:1024
	v_mfma_f32_32x32x16_bf16 v[82:97], v[174:177], v[158:161], v[82:97]
	global_load_lds_dwordx4 v[224:225], off offset:2048
	v_mfma_f32_32x32x16_bf16 v[50:65], v[170:173], v[158:161], v[50:65]
	global_load_lds_dwordx4 v[224:225], off offset:3072
	v_mfma_f32_32x32x16_bf16 v[18:33], v[174:177], v[162:165], v[18:33]
	s_add_i32 s10, s47, 0x6000
	s_cmpk_lg_u32 s47, 0xc000
	s_cselect_b32 s47, s10, 0
	s_add_i32 s10, s46, 0x6000
	s_cmpk_lg_u32 s46, 0xc000
	s_cselect_b32 s46, s10, 0
	v_mfma_f32_32x32x16_bf16 v[2:17], v[170:173], v[162:165], v[2:17]
	s_add_i32 s11, s47, 16
	s_waitcnt vmcnt(6) lgkmcnt(0)
	s_barrier
	v_add_u32_e32 v162, s11, v219
	v_add_u32_e32 v170, s11, v218
	v_add_u32_e32 v162, v162, v0
	v_add_u32_e32 v170, v170, v0
	ds_read_b128 v[158:161], v162
	ds_read_b128 v[182:185], v170 offset:8192
	ds_read_b128 v[178:181], v170 offset:10240
	ds_read_b128 v[162:165], v162 offset:2048
	ds_read_b128 v[174:177], v170 offset:12288
	ds_read_b128 v[170:173], v170 offset:14336
	v_mfma_f32_32x32x16_bf16 v[114:129], v[166:169], v[138:141], v[114:129]
	v_mfma_f32_32x32x16_bf16 v[98:113], v[154:157], v[138:141], v[98:113]
	v_mfma_f32_32x32x16_bf16 v[66:81], v[166:169], v[142:145], v[66:81]
	v_mfma_f32_32x32x16_bf16 v[34:49], v[154:157], v[142:145], v[34:49]
	v_mfma_f32_32x32x16_bf16 v[82:97], v[146:149], v[138:141], v[82:97]
	v_mfma_f32_32x32x16_bf16 v[50:65], v[150:153], v[138:141], v[50:65]
	v_mfma_f32_32x32x16_bf16 v[18:33], v[146:149], v[142:145], v[18:33]
	v_mfma_f32_32x32x16_bf16 v[2:17], v[150:153], v[142:145], v[2:17]
	s_add_i32 s42, s42, 2
	s_cmp_lg_u32 s42, 11
	s_cbranch_scc1 .LBB0_152
	s_add_i32 s11, s47, 16
	v_add_u32_e32 v142, s11, v219
	v_add_u32_e32 v150, s11, v218
	v_add_u32_e32 v142, v142, v220
	v_add_u32_e32 v150, v150, v220
	ds_read_b128 v[138:141], v142
	ds_read_b128 v[166:169], v150 offset:8192
	ds_read_b128 v[154:157], v150 offset:10240
	ds_read_b128 v[142:145], v142 offset:2048
	ds_read_b128 v[146:149], v150 offset:12288
	ds_read_b128 v[150:153], v150 offset:14336
	s_waitcnt lgkmcnt(6)
	v_mfma_f32_32x32x16_bf16 v[114:129], v[182:185], v[158:161], v[114:129]
	v_mfma_f32_32x32x16_bf16 v[98:113], v[178:181], v[158:161], v[98:113]
	v_mfma_f32_32x32x16_bf16 v[66:81], v[182:185], v[162:165], v[66:81]
	v_mfma_f32_32x32x16_bf16 v[34:49], v[178:181], v[162:165], v[34:49]
	v_mfma_f32_32x32x16_bf16 v[82:97], v[174:177], v[158:161], v[82:97]
	v_mfma_f32_32x32x16_bf16 v[50:65], v[170:173], v[158:161], v[50:65]
	v_mfma_f32_32x32x16_bf16 v[18:33], v[174:177], v[162:165], v[18:33]
	s_add_i32 s10, s47, 0x6000
	s_cmpk_lg_u32 s47, 0xc000
	s_cselect_b32 s47, s10, 0
	v_mfma_f32_32x32x16_bf16 v[2:17], v[170:173], v[162:165], v[2:17]
	s_add_i32 s11, s47, 16
	s_waitcnt vmcnt(0) lgkmcnt(0)
	s_barrier
; #define LAS __attribute__((address_space(3)))
; DI f32x16 mfma32(bf16x8 a, bf16x8 b, f32x16 c) { return __builtin_amdgcn_mfma_f32_32x32x16_bf16(a, b, c, 0, 0, 0); }
;     ...
;   for (int kt = 0; kt < nk; ++kt) {
;     const int kn = (kt + 2 < nk) ? (kt + 2) : (nk - 1);
;     const LAS char* cur = lds + s0;
;     bf16x8 af[2][2], bfr[2][4];
; #pragma unroll
;     for (int kk = 0; kk < 2; ++kk) {
;       const int xo = kk ? x1 : x0;
;       af[kk][0] = *(const LAS bf16x8*)(cur + a_rd + xo);
;       bfr[kk][0] = *(const LAS bf16x8*)(cur + b_rd + xo);
;       bfr[kk][1] = *(const LAS bf16x8*)(cur + b_rd + 2048 + xo);
;       af[kk][1] = *(const LAS bf16x8*)(cur + a_rd + 2048 + xo);
;       bfr[kk][2] = *(const LAS bf16x8*)(cur + b_rd + 4096 + xo);
;       bfr[kk][3] = *(const LAS bf16x8*)(cur + b_rd + 6144 + xo);
;     }
;     DMA_STEP_(kn, s2);
; #pragma unroll
;     for (int kk = 0; kk < 2; ++kk) {
;       acc[0][0] = mfma32(bfr[kk][0], af[kk][0], acc[0][0]); acc[0][1] = mfma32(bfr[kk][1], af[kk][0], acc[0][1]);
;       acc[1][0] = mfma32(bfr[kk][0], af[kk][1], acc[1][0]); acc[1][1] = mfma32(bfr[kk][1], af[kk][1], acc[1][1]);
;       acc[0][2] = mfma32(bfr[kk][2], af[kk][0], acc[0][2]); acc[0][3] = mfma32(bfr[kk][3], af[kk][0], acc[0][3]);
;       acc[1][2] = mfma32(bfr[kk][2], af[kk][1], acc[1][2]); acc[1][3] = mfma32(bfr[kk][3], af[kk][1], acc[1][3]);
;     }
;     __builtin_amdgcn_sched_group_barrier(0x100, 12, 0);
;     __builtin_amdgcn_sched_group_barrier(0x010, 6, 0);
;     __builtin_amdgcn_sched_group_barrier(0x008, 16, 0);
;     asm volatile("s_waitcnt vmcnt(6) lgkmcnt(0)" ::: "memory");
;     __builtin_amdgcn_s_barrier();
;     asm volatile("" ::: "memory");
;     s0 = (s0 == 2 * STG) ? 0 : s0 + STG;
;     s2 = (s2 == 2 * STG) ? 0 : s2 + STG;
;   }
;   asm volatile("s_waitcnt vmcnt(0)" ::: "memory");
;   __builtin_amdgcn_s_barrier();
;   asm volatile("" ::: "memory");
;     ...
;   {
;     const int h = lane >> 5, cl = lane & 31;
; #pragma unroll
;     for (int i = 0; i < 2; ++i)
; #pragma unroll
;       for (int j = 0; j < 4; ++j)
; #pragma unroll
;         for (int g = 0; g < 4; ++g) {
;           u32x2 w; w.x = pk2(acc[i][j][4 * g], acc[i][j][4 * g + 1]); w.y = pk2(acc[i][j][4 * g + 2], acc[i][j][4 * g + 3]);
;           *(u32x2*)(smem + (wr * 64 + i * 32 + cl) * 528 + (wc * 128 + j * 32 + 8 * g + 4 * h) * 2) = w;
;         }
;   }
;   __syncthreads();
	v_add_u32_e32 v162, s11, v219
	v_add_u32_e32 v170, s11, v218
	v_add_u32_e32 v162, v162, v0
	v_add_u32_e32 v170, v170, v0
	ds_read_b128 v[158:161], v162
	ds_read_b128 v[182:185], v170 offset:8192
	ds_read_b128 v[178:181], v170 offset:10240
	ds_read_b128 v[162:165], v162 offset:2048
	ds_read_b128 v[174:177], v170 offset:12288
	ds_read_b128 v[170:173], v170 offset:14336
	v_mfma_f32_32x32x16_bf16 v[114:129], v[166:169], v[138:141], v[114:129]
	v_mfma_f32_32x32x16_bf16 v[98:113], v[154:157], v[138:141], v[98:113]
	v_mfma_f32_32x32x16_bf16 v[66:81], v[166:169], v[142:145], v[66:81]
	v_mfma_f32_32x32x16_bf16 v[34:49], v[154:157], v[142:145], v[34:49]
	v_mfma_f32_32x32x16_bf16 v[82:97], v[146:149], v[138:141], v[82:97]
	v_mfma_f32_32x32x16_bf16 v[50:65], v[150:153], v[138:141], v[50:65]
	v_mfma_f32_32x32x16_bf16 v[18:33], v[146:149], v[142:145], v[18:33]
	v_mfma_f32_32x32x16_bf16 v[2:17], v[150:153], v[142:145], v[2:17]
	s_add_i32 s11, s47, 16
	v_add_u32_e32 v142, s11, v219
	v_add_u32_e32 v150, s11, v218
	v_add_u32_e32 v142, v142, v220
	v_add_u32_e32 v150, v150, v220
	ds_read_b128 v[138:141], v142
	ds_read_b128 v[166:169], v150 offset:8192
	ds_read_b128 v[154:157], v150 offset:10240
	ds_read_b128 v[142:145], v142 offset:2048
	ds_read_b128 v[146:149], v150 offset:12288
	ds_read_b128 v[150:153], v150 offset:14336
	s_waitcnt lgkmcnt(6)
	v_mfma_f32_32x32x16_bf16 v[114:129], v[182:185], v[158:161], v[114:129]
	v_mfma_f32_32x32x16_bf16 v[98:113], v[178:181], v[158:161], v[98:113]
	v_mfma_f32_32x32x16_bf16 v[66:81], v[182:185], v[162:165], v[66:81]
	v_mfma_f32_32x32x16_bf16 v[34:49], v[178:181], v[162:165], v[34:49]
	v_mfma_f32_32x32x16_bf16 v[82:97], v[174:177], v[158:161], v[82:97]
	v_mfma_f32_32x32x16_bf16 v[50:65], v[170:173], v[158:161], v[50:65]
	v_mfma_f32_32x32x16_bf16 v[18:33], v[174:177], v[162:165], v[18:33]
	v_mfma_f32_32x32x16_bf16 v[2:17], v[170:173], v[162:165], v[2:17]
	s_waitcnt lgkmcnt(0)
	v_mfma_f32_32x32x16_bf16 v[114:129], v[166:169], v[138:141], v[114:129]
	v_mfma_f32_32x32x16_bf16 v[98:113], v[154:157], v[138:141], v[98:113]
	v_mfma_f32_32x32x16_bf16 v[66:81], v[166:169], v[142:145], v[66:81]
	v_mfma_f32_32x32x16_bf16 v[34:49], v[154:157], v[142:145], v[34:49]
	v_mfma_f32_32x32x16_bf16 v[82:97], v[146:149], v[138:141], v[82:97]
	v_mfma_f32_32x32x16_bf16 v[50:65], v[150:153], v[138:141], v[50:65]
	v_mfma_f32_32x32x16_bf16 v[18:33], v[146:149], v[142:145], v[18:33]
	v_mfma_f32_32x32x16_bf16 v[2:17], v[150:153], v[142:145], v[2:17]
	s_waitcnt lgkmcnt(0)
	s_setprio 0
	v_mul_lo_u32 v0, v197, s55
	v_add_u32_e32 v0, 16, v0
	s_nop 1
	v_cvt_pk_bf16_f32 v114, v114, v115
	v_cvt_pk_bf16_f32 v115, v116, v117
	v_lshlrev_b32_e32 v116, 3, v196
	s_lshl_b32 s10, s43, 1
	v_add3_u32 v0, v0, v116, s10
	v_cvt_pk_bf16_f32 v116, v118, v119
	v_cvt_pk_bf16_f32 v117, v120, v121
	v_cvt_pk_bf16_f32 v98, v98, v99
	v_cvt_pk_bf16_f32 v99, v100, v101
	v_cvt_pk_bf16_f32 v100, v102, v103
	v_cvt_pk_bf16_f32 v101, v104, v105
	v_cvt_pk_bf16_f32 v82, v82, v83
	v_cvt_pk_bf16_f32 v83, v84, v85
	v_cvt_pk_bf16_f32 v84, v86, v87
	v_cvt_pk_bf16_f32 v85, v88, v89
	v_cvt_pk_bf16_f32 v50, v50, v51
	v_cvt_pk_bf16_f32 v51, v52, v53
	v_cvt_pk_bf16_f32 v52, v54, v55
	v_cvt_pk_bf16_f32 v53, v56, v57
	s_waitcnt vmcnt(0)
	s_barrier
	ds_write2_b64 v0, v[114:115], v[116:117] offset1:2
	v_cvt_pk_bf16_f32 v114, v122, v123
	v_cvt_pk_bf16_f32 v115, v124, v125
	v_cvt_pk_bf16_f32 v116, v126, v127
	v_cvt_pk_bf16_f32 v117, v128, v129
	ds_write2_b64 v0, v[98:99], v[100:101] offset0:8 offset1:10
	v_cvt_pk_bf16_f32 v98, v106, v107
	v_cvt_pk_bf16_f32 v99, v108, v109
	v_cvt_pk_bf16_f32 v100, v110, v111
	v_cvt_pk_bf16_f32 v101, v112, v113
	ds_write2_b64 v0, v[82:83], v[84:85] offset0:16 offset1:18
	v_cvt_pk_bf16_f32 v82, v90, v91
	v_cvt_pk_bf16_f32 v83, v92, v93
	v_cvt_pk_bf16_f32 v84, v94, v95
	v_cvt_pk_bf16_f32 v85, v96, v97
	ds_write2_b64 v0, v[50:51], v[52:53] offset0:24 offset1:26
	v_cvt_pk_bf16_f32 v50, v58, v59
	v_cvt_pk_bf16_f32 v51, v60, v61
	v_cvt_pk_bf16_f32 v52, v62, v63
	v_cvt_pk_bf16_f32 v53, v64, v65
	ds_write2_b64 v0, v[114:115], v[116:117] offset0:4 offset1:6
	ds_write2_b64 v0, v[98:99], v[100:101] offset0:12 offset1:14
	ds_write2_b64 v0, v[82:83], v[84:85] offset0:20 offset1:22
	ds_write2_b64 v0, v[50:51], v[52:53] offset0:28 offset1:30
	v_cvt_pk_bf16_f32 v50, v66, v67
	v_cvt_pk_bf16_f32 v51, v68, v69
	v_cvt_pk_bf16_f32 v52, v70, v71
	v_cvt_pk_bf16_f32 v53, v72, v73
	v_add_u32_e32 v0, 0x4000, v0
	v_cvt_pk_bf16_f32 v34, v34, v35
	v_cvt_pk_bf16_f32 v35, v36, v37
	v_cvt_pk_bf16_f32 v36, v38, v39
	v_cvt_pk_bf16_f32 v37, v40, v41
	v_cvt_pk_bf16_f32 v18, v18, v19
	v_cvt_pk_bf16_f32 v19, v20, v21
	v_cvt_pk_bf16_f32 v20, v22, v23
	v_cvt_pk_bf16_f32 v21, v24, v25
	v_cvt_pk_bf16_f32 v2, v2, v3
	v_cvt_pk_bf16_f32 v3, v4, v5
	v_cvt_pk_bf16_f32 v4, v6, v7
	v_cvt_pk_bf16_f32 v5, v8, v9
	ds_write2_b64 v0, v[50:51], v[52:53] offset0:64 offset1:66
	v_cvt_pk_bf16_f32 v50, v74, v75
	v_cvt_pk_bf16_f32 v51, v76, v77
	v_cvt_pk_bf16_f32 v52, v78, v79
	v_cvt_pk_bf16_f32 v53, v80, v81
	ds_write2_b64 v0, v[34:35], v[36:37] offset0:72 offset1:74
	v_cvt_pk_bf16_f32 v34, v42, v43
	v_cvt_pk_bf16_f32 v35, v44, v45
	v_cvt_pk_bf16_f32 v36, v46, v47
	v_cvt_pk_bf16_f32 v37, v48, v49
	ds_write2_b64 v0, v[18:19], v[20:21] offset0:80 offset1:82
	v_cvt_pk_bf16_f32 v18, v26, v27
	v_cvt_pk_bf16_f32 v19, v28, v29
	v_cvt_pk_bf16_f32 v20, v30, v31
	v_cvt_pk_bf16_f32 v21, v32, v33
	ds_write2_b64 v0, v[2:3], v[4:5] offset0:88 offset1:90
	v_cvt_pk_bf16_f32 v2, v10, v11
	v_cvt_pk_bf16_f32 v3, v12, v13
	v_cvt_pk_bf16_f32 v4, v14, v15
	v_cvt_pk_bf16_f32 v5, v16, v17
	s_lshl_b64 s[12:13], s[12:13], 1
	ds_write2_b64 v0, v[50:51], v[52:53] offset0:68 offset1:70
	ds_write2_b64 v0, v[34:35], v[36:37] offset0:76 offset1:78
	ds_write2_b64 v0, v[18:19], v[20:21] offset0:84 offset1:86
	ds_write2_b64 v0, v[2:3], v[4:5] offset0:92 offset1:94
	s_waitcnt vmcnt(0) lgkmcnt(0)
	s_barrier
; #define GAS __attribute__((address_space(1)))
;     ...
;   if (EPI == 0) {
; #pragma unroll
;     for (int i = 0; i < 16; ++i) {
;       const int id = tid2 + 256 * i, r = id >> 5, c8 = (id & 31) * 8;
;       const u32x4 v = *(const u32x4*)(smem + r * 528 + c8 * 2);
;       *(GAS u32x4*)(ea.out + (size_t)(m0 + r) * ea.ldo + n0 + c8) = v;
;     }
	s_add_u32 s12, s14, s12
	v_lshlrev_b32_e32 v0, 4, v189
	v_and_b32_e32 v0, 0x1f0, v0
	s_addc_u32 s13, s15, s13
	v_add_u32_e32 v10, 16, v0
	v_lshl_add_u64 v[12:13], s[12:13], 0, v[0:1]
	v_ashrrev_i32_e32 v0, 5, v189
	v_mad_u64_u32 v[2:3], s[12:13], v0, s55, v[10:11]
	v_add_u32_e32 v0, s41, v0
	s_movk_i32 s10, 0x600
	v_mad_i64_i32 v[14:15], s[12:13], v0, s10, v[12:13]
	v_add_u32_e32 v0, 0x100, v189
	ds_read_b128 v[2:5], v2
	v_ashrrev_i32_e32 v0, 5, v0
	v_mad_u64_u32 v[6:7], s[12:13], v0, s55, v[10:11]
	ds_read_b128 v[6:9], v6
	v_add_u32_e32 v0, s41, v0
	s_waitcnt lgkmcnt(1)
	global_store_dwordx4 v[14:15], v[2:5], off
	v_readlane_b32 s44, v250, 17
	s_nop 0
	v_mad_i64_i32 v[2:3], s[12:13], v0, s10, v[12:13]
	v_add_u32_e32 v0, 0x200, v189
	v_ashrrev_i32_e32 v0, 5, v0
	s_waitcnt lgkmcnt(0)
	global_store_dwordx4 v[2:3], v[6:9], off
	v_mad_u64_u32 v[2:3], s[12:13], v0, s55, v[10:11]
	v_add_u32_e32 v0, s41, v0
	v_mad_i64_i32 v[14:15], s[12:13], v0, s10, v[12:13]
	v_add_u32_e32 v0, 0x300, v189
	ds_read_b128 v[2:5], v2
	v_ashrrev_i32_e32 v0, 5, v0
	v_mad_u64_u32 v[6:7], s[12:13], v0, s55, v[10:11]
	ds_read_b128 v[6:9], v6
	v_add_u32_e32 v0, s41, v0
	s_waitcnt lgkmcnt(1)
	global_store_dwordx4 v[14:15], v[2:5], off
	s_nop 1
	v_mad_i64_i32 v[2:3], s[12:13], v0, s10, v[12:13]
	v_add_u32_e32 v0, 0x400, v189
	v_ashrrev_i32_e32 v0, 5, v0
	s_waitcnt lgkmcnt(0)
	global_store_dwordx4 v[2:3], v[6:9], off
	v_mad_u64_u32 v[2:3], s[12:13], v0, s55, v[10:11]
	v_add_u32_e32 v0, s41, v0
	v_mad_i64_i32 v[14:15], s[12:13], v0, s10, v[12:13]
	v_add_u32_e32 v0, 0x500, v189
	ds_read_b128 v[2:5], v2
	v_ashrrev_i32_e32 v0, 5, v0
	v_mad_u64_u32 v[6:7], s[12:13], v0, s55, v[10:11]
	ds_read_b128 v[6:9], v6
	v_add_u32_e32 v0, s41, v0
	s_waitcnt lgkmcnt(1)
	global_store_dwordx4 v[14:15], v[2:5], off
	s_nop 1
	v_mad_i64_i32 v[2:3], s[12:13], v0, s10, v[12:13]
	v_add_u32_e32 v0, 0x600, v189
	v_ashrrev_i32_e32 v0, 5, v0
	s_waitcnt lgkmcnt(0)
	global_store_dwordx4 v[2:3], v[6:9], off
	v_mad_u64_u32 v[2:3], s[12:13], v0, s55, v[10:11]
	v_add_u32_e32 v0, s41, v0
	v_mad_i64_i32 v[14:15], s[12:13], v0, s10, v[12:13]
	v_add_u32_e32 v0, 0x700, v189
	ds_read_b128 v[2:5], v2
	v_ashrrev_i32_e32 v0, 5, v0
	v_mad_u64_u32 v[6:7], s[12:13], v0, s55, v[10:11]
	ds_read_b128 v[6:9], v6
	v_add_u32_e32 v0, s41, v0
	s_waitcnt lgkmcnt(1)
	global_store_dwordx4 v[14:15], v[2:5], off
	s_nop 1
	v_mad_i64_i32 v[2:3], s[12:13], v0, s10, v[12:13]
	v_add_u32_e32 v0, 0x800, v189
	v_ashrrev_i32_e32 v0, 5, v0
	s_waitcnt lgkmcnt(0)
	global_store_dwordx4 v[2:3], v[6:9], off
	v_mad_u64_u32 v[2:3], s[12:13], v0, s55, v[10:11]
	v_add_u32_e32 v0, s41, v0
	v_mad_i64_i32 v[14:15], s[12:13], v0, s10, v[12:13]
	v_add_u32_e32 v0, 0x900, v189
	ds_read_b128 v[2:5], v2
	v_ashrrev_i32_e32 v0, 5, v0
	v_mad_u64_u32 v[6:7], s[12:13], v0, s55, v[10:11]
	ds_read_b128 v[6:9], v6
	v_add_u32_e32 v0, s41, v0
	s_waitcnt lgkmcnt(1)
	global_store_dwordx4 v[14:15], v[2:5], off
	s_nop 1
	v_mad_i64_i32 v[2:3], s[12:13], v0, s10, v[12:13]
	v_add_u32_e32 v0, 0xa00, v189
	v_ashrrev_i32_e32 v0, 5, v0
	s_waitcnt lgkmcnt(0)
	global_store_dwordx4 v[2:3], v[6:9], off
	v_mad_u64_u32 v[2:3], s[12:13], v0, s55, v[10:11]
	v_add_u32_e32 v0, s41, v0
	v_mad_i64_i32 v[14:15], s[12:13], v0, s10, v[12:13]
	v_add_u32_e32 v0, 0xb00, v189
	ds_read_b128 v[2:5], v2
	v_ashrrev_i32_e32 v0, 5, v0
	v_mad_u64_u32 v[6:7], s[12:13], v0, s55, v[10:11]
	ds_read_b128 v[6:9], v6
	v_add_u32_e32 v0, s41, v0
	s_waitcnt lgkmcnt(1)
	global_store_dwordx4 v[14:15], v[2:5], off
	s_nop 1
	v_mad_i64_i32 v[2:3], s[12:13], v0, s10, v[12:13]
	v_add_u32_e32 v0, 0xc00, v189
	v_ashrrev_i32_e32 v0, 5, v0
	s_waitcnt lgkmcnt(0)
	global_store_dwordx4 v[2:3], v[6:9], off
	v_mad_u64_u32 v[2:3], s[12:13], v0, s55, v[10:11]
	v_add_u32_e32 v0, s41, v0
	v_mad_i64_i32 v[14:15], s[12:13], v0, s10, v[12:13]
	v_add_u32_e32 v0, 0xd00, v189
	ds_read_b128 v[2:5], v2
	v_ashrrev_i32_e32 v0, 5, v0
	v_mad_u64_u32 v[6:7], s[12:13], v0, s55, v[10:11]
	ds_read_b128 v[6:9], v6
	v_add_u32_e32 v0, s41, v0
	s_waitcnt lgkmcnt(1)
	global_store_dwordx4 v[14:15], v[2:5], off
	s_nop 1
	v_mad_i64_i32 v[2:3], s[12:13], v0, s10, v[12:13]
	v_add_u32_e32 v0, 0xe00, v189
	v_ashrrev_i32_e32 v0, 5, v0
	s_waitcnt lgkmcnt(0)
	global_store_dwordx4 v[2:3], v[6:9], off
	v_mad_u64_u32 v[2:3], s[12:13], v0, s55, v[10:11]
	v_add_u32_e32 v0, s41, v0
	v_mad_i64_i32 v[14:15], s[12:13], v0, s10, v[12:13]
	v_add_u32_e32 v0, 0xf00, v189
	v_ashrrev_i32_e32 v0, 5, v0
	ds_read_b128 v[2:5], v2
	v_mad_u64_u32 v[6:7], s[12:13], v0, s55, v[10:11]
	ds_read_b128 v[6:9], v6
	v_add_u32_e32 v0, s41, v0
	s_waitcnt lgkmcnt(1)
	global_store_dwordx4 v[14:15], v[2:5], off
	s_nop 1
	v_mad_i64_i32 v[2:3], s[12:13], v0, s10, v[12:13]
	s_waitcnt lgkmcnt(0)
	global_store_dwordx4 v[2:3], v[6:9], off
	s_barrier
	s_branch .LBB0_145

; #define GAS __attribute__((address_space(1)))
; DI unsigned pk2(float a, float b) { f32x2 v = {a, b}; bf2_t r = __builtin_convertvector(v, bf2_t); return __builtin_bit_cast(unsigned, r); }
; DI void wt_item(const float* __restrict__ W, int ldw, int K, bf16_t* __restrict__ Wt, int k0, int d0, int mode, char* smem, int tid) {
;     ...
; #pragma unroll
;   for (int u = 0; u < 2; ++u) {
;     const int id = tid + 256 * u, j = id >> 3, k8 = (id & 7) * 8;
;     float v[8];
; #pragma unroll
;     for (int e = 0; e < 8; ++e) v[e] = tile[(k8 + e) * 65 + j];
;     u32x4 w; w.x = pk2(v[0], v[1]); w.y = pk2(v[2], v[3]); w.z = pk2(v[4], v[5]); w.w = pk2(v[6], v[7]);
;     *(GAS u32x4*)(Wt + (size_t)(d0 + j) * K + k0 + k8) = w;
;   }
.LBB0_461:
	s_or_b64 exec, exec, s[18:19]
	v_readlane_b32 s10, v250, 18
	ds_write_b32 v66, v0 offset:14560
	ds_write_b32 v66, v7 offset:15600
	v_add_u32_e32 v0, 0x400, v64
	v_readlane_b32 s11, v250, 19
	s_add_u32 s10, s10, s48
	s_waitcnt lgkmcnt(0)
	s_barrier
	ds_read2_b32 v[8:9], v64 offset1:65
	ds_read2_b32 v[10:11], v64 offset0:130 offset1:195
	ds_read2_b32 v[12:13], v0 offset0:4 offset1:69
	ds_read2_b32 v[14:15], v0 offset0:134 offset1:199
	s_addc_u32 s11, s11, s49
	s_cmp_eq_u32 s48, 0x1f90000
	s_cbranch_scc1 .Lmy_wt_new
	s_cmp_eq_u32 s48, 0x2510000
	s_cbranch_scc1 .Lmy_wt_new
	s_cmp_eq_u32 s48, 0x0
	s_cbranch_scc1 .Lmy_wt_new
	s_cmp_eq_u32 s48, 0x2a90000
	s_cbranch_scc1 .Lmy_wt_new
	s_cmp_eq_u32 s48, 0x590000
	s_cbranch_scc1 .Lmy_wt_new
	s_cmp_eq_u32 s48, 0x790000
	s_cbranch_scc1 .Lmy_wt_new
	s_cmp_eq_u32 s48, 0x510000
	s_cbranch_scc1 .Lmy_wt_new
	s_cmp_eq_u32 s48, 0x990000
	s_cbranch_scc1 .Lmy_wt_new
	s_cmp_eq_u32 s48, 0x1490000
	s_cbranch_scc1 .Lmy_wt_new
	s_cmp_eq_u32 s48, 0x480000
	s_cbranch_scc1 .Lmy_wt_new
	s_lshl_b32 s18, s22, 1
	s_add_u32 s18, s10, s18
	s_addc_u32 s19, s11, 0
	v_mov_b32_e32 v7, v1
	v_add_u32_e32 v0, s15, v61
	v_lshl_add_u64 v[16:17], s[18:19], 0, v[6:7]
	v_ashrrev_i32_e32 v7, 31, v0
	s_waitcnt lgkmcnt(0)
	v_cvt_pk_bf16_f32 v8, v8, v9
	v_cvt_pk_bf16_f32 v9, v10, v11
	v_cvt_pk_bf16_f32 v10, v12, v13
	v_cvt_pk_bf16_f32 v11, v14, v15
	v_mul_lo_u32 v7, s46, v7
	v_mul_lo_u32 v14, s47, v0
	v_mad_u64_u32 v[12:13], s[18:19], s46, v0, 0
	v_add3_u32 v13, v13, v7, v14
	ds_read2_b32 v[14:15], v65 offset1:65
	ds_read2_b32 v[18:19], v65 offset0:130 offset1:195
	v_add_u32_e32 v0, 0x400, v65
	ds_read2_b32 v[20:21], v0 offset0:4 offset1:69
	ds_read2_b32 v[22:23], v0 offset0:134 offset1:199
	v_add_u32_e32 v0, s15, v62
	v_lshl_add_u64 v[12:13], v[12:13], 1, v[16:17]
	v_ashrrev_i32_e32 v7, 31, v0
	global_store_dwordx4 v[12:13], v[8:11], off
	v_mul_lo_u32 v7, s46, v7
	v_mad_u64_u32 v[12:13], s[18:19], s46, v0, 0
	s_waitcnt lgkmcnt(0)
	v_cvt_pk_bf16_f32 v8, v14, v15
	v_mul_lo_u32 v14, s47, v0
	v_add3_u32 v13, v13, v7, v14
	v_cvt_pk_bf16_f32 v9, v18, v19
	v_cvt_pk_bf16_f32 v10, v20, v21
	v_cvt_pk_bf16_f32 v11, v22, v23
	v_lshl_add_u64 v[12:13], v[12:13], 1, v[16:17]
	global_store_dwordx4 v[12:13], v[8:11], off
	s_branch .Lmy_wt_done
